# job queue: next ticket requested after the gate loads are issued (so the first gate group does not wait for the atomic)
# baseline (speedup 1.0000x reference)
.LBB0_411:
	v_mbcnt_lo_u32_b32 v0, -1, 0
	v_mbcnt_hi_u32_b32 v0, -1, v0
	v_and_b32_e32 v2, 64, v0
	v_xor_b32_e32 v1, 32, v0
	v_add_u32_e32 v2, 64, v2
	v_cmp_lt_i32_e32 vcc, v1, v2
	s_movk_i32 s8, 0x1d00
	v_mov_b32_e32 v141, v193
	v_cndmask_b32_e32 v0, v0, v1, vcc
	v_lshlrev_b32_e32 v0, 2, v0
	ds_bpermute_b32 v0, v0, v163
	s_waitcnt lgkmcnt(0)
	v_add_f32_e32 v0, v163, v0
	v_div_scale_f32 v1, s[0:1], v0, v0, 1.0
	v_rcp_f32_e32 v2, v1
	v_readlane_b32 s0, v254, 43
	v_readlane_b32 s1, v254, 44
	v_fma_f32 v3, -v1, v2, 1.0
	v_fmac_f32_e32 v2, v3, v2
	v_div_scale_f32 v3, vcc, 1.0, v0, 1.0
	v_mul_f32_e32 v4, v3, v2
	v_fma_f32 v5, -v1, v4, v3
	v_fmac_f32_e32 v4, v5, v2
	v_fma_f32 v1, -v1, v4, v3
	v_div_fmas_f32 v1, v1, v2, v4
	v_div_fixup_f32 v4, v1, v0, 1.0
	v_mov_b64_e32 v[0:1], s[0:1]
	v_mad_u64_u32 v[0:1], s[0:1], v142, s8, v[0:1]
	v_mad_i32_i24 v1, v143, s8, v1
	s_mov_b64 s[8:9], 0x3e38aa3b
	s_lshl_b32 s0, s10, 1
	s_mov_b32 s1, s9
	s_movk_i32 s10, 0xeb00
	v_lshl_add_u64 v[2:3], v[0:1], 0, s[0:1]
	v_mad_u64_u32 v[0:1], s[8:9], v142, s10, v[0:1]
	v_mad_i32_i24 v1, v143, s10, v1
	v_sub_u32_e32 v1, v1, v142
	v_lshl_add_u64 v[6:7], v[0:1], 0, s[0:1]
	v_lshl_add_u64 v[2:3], v[2:3], 0, v[140:141]
	s_mov_b64 s[0:1], 0x3dd0b00
	v_lshl_add_u64 v[0:1], v[2:3], 0, s[0:1]
	v_lshl_add_u64 v[12:13], v[6:7], 0, v[140:141]
	s_mov_b64 s[0:1], 0xd210200
	v_lshl_add_u64 v[6:7], v[12:13], 0, s[0:1]
	s_mov_b32 s0, 0x3dd0000
	v_add_co_u32_e32 v2, vcc, s0, v2
	v_readlane_b32 s10, v254, 51
	s_nop 0
	v_addc_co_u32_e32 v3, vcc, 0, v3, vcc
	global_load_dwordx4 v[8:11], v[2:3], off offset:2816
	global_load_dwordx4 v[64:67], v[0:1], off offset:32
	global_load_dwordx4 v[68:71], v[0:1], off offset:64
	global_load_dwordx4 v[72:75], v[0:1], off offset:96
	v_readlane_b32 s98, v253, 59
	v_readlane_b32 s99, v253, 60
	s_nop 1
	v_writelane_b32 v76, s98, 40
	v_writelane_b32 v77, s99, 40
	s_mov_b64 s[98:99], exec
	v_cmpx_eq_u32_e64 exec, 40, v234
	s_nop 3
	v_writelane_b32 v255, exec_hi, 41
	global_atomic_add v255, v[76:77], v251, off sc0
	s_mov_b64 exec, s[98:99]
	s_waitcnt vmcnt(3)
	v_mov_b32_e32 v5, v10
	s_nop 1
	v_permlane32_swap_b32_e32 v8, v5
	v_lshlrev_b32_e32 v14, 16, v8
	v_and_b32_e32 v8, 0xffff0000, v8
	v_mov_b32_e32 v16, v11
	v_mul_f32_e32 v10, 0xbfb8aa3b, v14
	v_mul_f32_e32 v11, 0xbfb8aa3b, v8
	v_exp_f32_e32 v10, v10
	v_exp_f32_e32 v11, v11
	v_permlane32_swap_b32_e32 v9, v16
	v_pk_mul_f32 v[2:3], v[48:49], v[4:5] op_sel_hi:[1,0]
	v_pk_add_f32 v[10:11], v[10:11], 1.0 op_sel_hi:[1,0]
	s_nop 0
	v_div_scale_f32 v15, s[0:1], v11, v11, v8
	v_rcp_f32_e32 v17, v15
	s_nop 0
	v_fma_f32 v18, -v15, v17, 1.0
	v_fmac_f32_e32 v17, v18, v17
	v_div_scale_f32 v18, vcc, v8, v11, v8
	v_mul_f32_e32 v19, v18, v17
	v_fma_f32 v20, -v15, v19, v18
	v_fmac_f32_e32 v19, v20, v17
	v_fma_f32 v15, -v15, v19, v18
	v_div_fmas_f32 v15, v15, v17, v19
	v_div_fixup_f32 v11, v15, v11, v8
	v_div_scale_f32 v8, s[0:1], v10, v10, v14
	v_rcp_f32_e32 v15, v8
	s_nop 0
	v_fma_f32 v17, -v8, v15, 1.0
	v_fmac_f32_e32 v15, v17, v15
	v_div_scale_f32 v17, vcc, v14, v10, v14
	v_mul_f32_e32 v18, v17, v15
	v_fma_f32 v19, -v8, v18, v17
	v_fmac_f32_e32 v18, v19, v15
	v_fma_f32 v8, -v8, v18, v17
	v_div_fmas_f32 v8, v8, v15, v18
	v_div_fixup_f32 v10, v8, v10, v14
	v_lshlrev_b32_e32 v14, 16, v9
	v_and_b32_e32 v15, 0xffff0000, v9
	v_pk_mul_f32 v[2:3], v[2:3], v[10:11]
	v_mul_f32_e32 v10, 0xbfb8aa3b, v14
	v_mul_f32_e32 v11, 0xbfb8aa3b, v15
	v_exp_f32_e32 v10, v10
	v_exp_f32_e32 v11, v11
	v_pk_mul_f32 v[8:9], v[50:51], v[4:5] op_sel_hi:[1,0]
	v_pk_add_f32 v[10:11], v[10:11], 1.0 op_sel_hi:[1,0]
	s_nop 0
	v_div_scale_f32 v17, s[0:1], v11, v11, v15
	v_rcp_f32_e32 v18, v17
	s_nop 0
	v_fma_f32 v19, -v17, v18, 1.0
	v_fmac_f32_e32 v18, v19, v18
	v_div_scale_f32 v19, vcc, v15, v11, v15
	v_mul_f32_e32 v20, v19, v18
	v_fma_f32 v21, -v17, v20, v19
	v_fmac_f32_e32 v20, v21, v18
	v_fma_f32 v17, -v17, v20, v19
	v_div_fmas_f32 v17, v17, v18, v20
	v_div_fixup_f32 v11, v17, v11, v15
	v_div_scale_f32 v15, s[0:1], v10, v10, v14
	v_rcp_f32_e32 v17, v15
	s_nop 0
	v_fma_f32 v18, -v15, v17, 1.0
	v_fmac_f32_e32 v17, v18, v17
	v_div_scale_f32 v18, vcc, v14, v10, v14
	v_mul_f32_e32 v19, v18, v17
	v_fma_f32 v20, -v15, v19, v18
	v_fmac_f32_e32 v19, v20, v17
	v_fma_f32 v15, -v15, v19, v18
	v_div_fmas_f32 v15, v15, v17, v19
	v_lshlrev_b32_e32 v17, 16, v5
	v_and_b32_e32 v5, 0xffff0000, v5
	v_div_fixup_f32 v10, v15, v10, v14
	v_mul_f32_e32 v14, 0xbfb8aa3b, v17
	v_mul_f32_e32 v15, 0xbfb8aa3b, v5
	v_exp_f32_e32 v14, v14
	v_exp_f32_e32 v15, v15
	v_pk_mul_f32 v[10:11], v[8:9], v[10:11]
	v_pk_mul_f32 v[8:9], v[52:53], v[4:5] op_sel_hi:[1,0]
	v_pk_add_f32 v[14:15], v[14:15], 1.0 op_sel_hi:[1,0]
	s_nop 0
	v_div_scale_f32 v18, s[0:1], v15, v15, v5
	v_rcp_f32_e32 v19, v18
	s_nop 0
	v_fma_f32 v20, -v18, v19, 1.0
	v_fmac_f32_e32 v19, v20, v19
	v_div_scale_f32 v20, vcc, v5, v15, v5
	v_mul_f32_e32 v21, v20, v19
	v_fma_f32 v22, -v18, v21, v20
	v_fmac_f32_e32 v21, v22, v19
	v_fma_f32 v18, -v18, v21, v20
	v_div_fmas_f32 v18, v18, v19, v21
	v_div_fixup_f32 v15, v18, v15, v5
	v_div_scale_f32 v5, s[0:1], v14, v14, v17
	v_rcp_f32_e32 v18, v5
	s_nop 0
	v_fma_f32 v19, -v5, v18, 1.0
	v_fmac_f32_e32 v18, v19, v18
	v_div_scale_f32 v19, vcc, v17, v14, v17
	v_mul_f32_e32 v20, v19, v18
	v_fma_f32 v21, -v5, v20, v19
	v_fmac_f32_e32 v20, v21, v18
	v_fma_f32 v5, -v5, v20, v19
	v_div_fmas_f32 v5, v5, v18, v20
	v_div_fixup_f32 v14, v5, v14, v17
	v_lshlrev_b32_e32 v5, 16, v16
	v_and_b32_e32 v18, 0xffff0000, v16
	v_mul_f32_e32 v16, 0xbfb8aa3b, v5
	v_mul_f32_e32 v17, 0xbfb8aa3b, v18
	v_exp_f32_e32 v16, v16
	v_exp_f32_e32 v17, v17
	v_pk_mul_f32 v[14:15], v[8:9], v[14:15]
	v_pk_mul_f32 v[8:9], v[54:55], v[4:5] op_sel_hi:[1,0]
	v_pk_add_f32 v[16:17], v[16:17], 1.0 op_sel_hi:[1,0]
	s_nop 0
	v_div_scale_f32 v19, s[0:1], v17, v17, v18
	v_rcp_f32_e32 v20, v19
	s_nop 0
	v_fma_f32 v21, -v19, v20, 1.0
	v_fmac_f32_e32 v20, v21, v20
	v_div_scale_f32 v21, vcc, v18, v17, v18
	v_mul_f32_e32 v22, v21, v20
	v_fma_f32 v23, -v19, v22, v21
	v_fmac_f32_e32 v22, v23, v20
	v_fma_f32 v19, -v19, v22, v21
	v_div_fmas_f32 v19, v19, v20, v22
	v_div_fixup_f32 v17, v19, v17, v18
	v_div_scale_f32 v18, s[0:1], v16, v16, v5
	v_rcp_f32_e32 v19, v18
	s_mov_b32 s0, 0xd210000
	v_fma_f32 v20, -v18, v19, 1.0
	v_fmac_f32_e32 v19, v20, v19
	v_div_scale_f32 v20, vcc, v5, v16, v5
	v_mul_f32_e32 v21, v20, v19
	v_fma_f32 v22, -v18, v21, v20
	v_fmac_f32_e32 v21, v22, v19
	v_fma_f32 v18, -v18, v21, v20
	v_div_fmas_f32 v18, v18, v19, v21
	v_div_fixup_f32 v16, v18, v16, v5
	v_pk_mul_f32 v[16:17], v[8:9], v[16:17]
	v_cvt_pk_bf16_f32 v8, v2, v3
	v_cvt_pk_bf16_f32 v9, v10, v11
	v_cvt_pk_bf16_f32 v10, v14, v15
	v_cvt_pk_bf16_f32 v11, v16, v17
	v_add_co_u32_e32 v2, vcc, s0, v12
	v_permlane32_swap_b32_e32 v8, v10
	v_permlane32_swap_b32_e32 v9, v11
	v_addc_co_u32_e32 v3, vcc, 0, v13, vcc
	global_store_dwordx4 v[2:3], v[8:11], off offset:512
	s_waitcnt vmcnt(3)
	v_mov_b32_e32 v5, v66
	s_nop 1
	v_mov_b32_e32 v8, v64
	s_nop 1
	v_permlane32_swap_b32_e32 v8, v5
	v_lshlrev_b32_e32 v12, 16, v8
	v_and_b32_e32 v8, 0xffff0000, v8
	v_mov_b32_e32 v14, v67
	v_mul_f32_e32 v10, 0xbfb8aa3b, v12
	v_mul_f32_e32 v11, 0xbfb8aa3b, v8
	v_exp_f32_e32 v10, v10
	v_exp_f32_e32 v11, v11
	v_mov_b32_e32 v9, v65
	s_nop 1
	v_permlane32_swap_b32_e32 v9, v14
	v_pk_mul_f32 v[2:3], v[56:57], v[4:5] op_sel_hi:[1,0]
	v_pk_add_f32 v[10:11], v[10:11], 1.0 op_sel_hi:[1,0]
	s_nop 0
	v_div_scale_f32 v13, s[0:1], v11, v11, v8
	v_rcp_f32_e32 v15, v13
	s_nop 0
	v_fma_f32 v16, -v13, v15, 1.0
	v_fmac_f32_e32 v15, v16, v15
	v_div_scale_f32 v16, vcc, v8, v11, v8
	v_mul_f32_e32 v17, v16, v15
	v_fma_f32 v18, -v13, v17, v16
	v_fmac_f32_e32 v17, v18, v15
	v_fma_f32 v13, -v13, v17, v16
	v_div_fmas_f32 v13, v13, v15, v17
	v_div_fixup_f32 v11, v13, v11, v8
	v_div_scale_f32 v8, s[0:1], v10, v10, v12
	v_rcp_f32_e32 v13, v8
	s_nop 0
	v_fma_f32 v15, -v8, v13, 1.0
	v_fmac_f32_e32 v13, v15, v13
	v_div_scale_f32 v15, vcc, v12, v10, v12
	v_mul_f32_e32 v16, v15, v13
	v_fma_f32 v17, -v8, v16, v15
	v_fmac_f32_e32 v16, v17, v13
	v_fma_f32 v8, -v8, v16, v15
	v_div_fmas_f32 v8, v8, v13, v16
	v_div_fixup_f32 v10, v8, v10, v12
	v_lshlrev_b32_e32 v12, 16, v9
	v_and_b32_e32 v13, 0xffff0000, v9
	v_pk_mul_f32 v[2:3], v[2:3], v[10:11]
	v_mul_f32_e32 v10, 0xbfb8aa3b, v12
	v_mul_f32_e32 v11, 0xbfb8aa3b, v13
	v_exp_f32_e32 v10, v10
	v_exp_f32_e32 v11, v11
	v_pk_mul_f32 v[8:9], v[58:59], v[4:5] op_sel_hi:[1,0]
	v_pk_add_f32 v[10:11], v[10:11], 1.0 op_sel_hi:[1,0]
	s_nop 0
	v_div_scale_f32 v15, s[0:1], v11, v11, v13
	v_rcp_f32_e32 v16, v15
	s_nop 0
	v_fma_f32 v17, -v15, v16, 1.0
	v_fmac_f32_e32 v16, v17, v16
	v_div_scale_f32 v17, vcc, v13, v11, v13
	v_mul_f32_e32 v18, v17, v16
	v_fma_f32 v19, -v15, v18, v17
	v_fmac_f32_e32 v18, v19, v16
	v_fma_f32 v15, -v15, v18, v17
	v_div_fmas_f32 v15, v15, v16, v18
	v_div_fixup_f32 v11, v15, v11, v13
	v_div_scale_f32 v13, s[0:1], v10, v10, v12
	v_rcp_f32_e32 v15, v13
	s_nop 0
	v_fma_f32 v16, -v13, v15, 1.0
	v_fmac_f32_e32 v15, v16, v15
	v_div_scale_f32 v16, vcc, v12, v10, v12
	v_mul_f32_e32 v17, v16, v15
	v_fma_f32 v18, -v13, v17, v16
	v_fmac_f32_e32 v17, v18, v15
	v_fma_f32 v13, -v13, v17, v16
	v_div_fmas_f32 v13, v13, v15, v17
	v_lshlrev_b32_e32 v15, 16, v5
	v_and_b32_e32 v5, 0xffff0000, v5
	v_div_fixup_f32 v10, v13, v10, v12
	v_mul_f32_e32 v12, 0xbfb8aa3b, v15
	v_mul_f32_e32 v13, 0xbfb8aa3b, v5
	v_exp_f32_e32 v12, v12
	v_exp_f32_e32 v13, v13
	v_pk_mul_f32 v[10:11], v[8:9], v[10:11]
	v_pk_mul_f32 v[8:9], v[60:61], v[4:5] op_sel_hi:[1,0]
	v_pk_add_f32 v[12:13], v[12:13], 1.0 op_sel_hi:[1,0]
	s_nop 0
	v_div_scale_f32 v16, s[0:1], v13, v13, v5
	v_rcp_f32_e32 v17, v16
	s_nop 0
	v_fma_f32 v18, -v16, v17, 1.0
	v_fmac_f32_e32 v17, v18, v17
	v_div_scale_f32 v18, vcc, v5, v13, v5
	v_mul_f32_e32 v19, v18, v17
	v_fma_f32 v20, -v16, v19, v18
	v_fmac_f32_e32 v19, v20, v17
	v_fma_f32 v16, -v16, v19, v18
	v_div_fmas_f32 v16, v16, v17, v19
	v_div_fixup_f32 v13, v16, v13, v5
	v_div_scale_f32 v5, s[0:1], v12, v12, v15
	v_rcp_f32_e32 v16, v5
	s_nop 0
	v_fma_f32 v17, -v5, v16, 1.0
	v_fmac_f32_e32 v16, v17, v16
	v_div_scale_f32 v17, vcc, v15, v12, v15
	v_mul_f32_e32 v18, v17, v16
	v_fma_f32 v19, -v5, v18, v17
	v_fmac_f32_e32 v18, v19, v16
	v_fma_f32 v5, -v5, v18, v17
	v_div_fmas_f32 v5, v5, v16, v18
	v_div_fixup_f32 v12, v5, v12, v15
	v_lshlrev_b32_e32 v5, 16, v14
	v_and_b32_e32 v16, 0xffff0000, v14
	v_mul_f32_e32 v14, 0xbfb8aa3b, v5
	v_mul_f32_e32 v15, 0xbfb8aa3b, v16
	v_exp_f32_e32 v14, v14
	v_exp_f32_e32 v15, v15
	v_pk_mul_f32 v[12:13], v[8:9], v[12:13]
	v_pk_mul_f32 v[8:9], v[62:63], v[4:5] op_sel_hi:[1,0]
	v_pk_add_f32 v[14:15], v[14:15], 1.0 op_sel_hi:[1,0]
	s_nop 0
	v_div_scale_f32 v17, s[0:1], v15, v15, v16
	v_rcp_f32_e32 v18, v17
	s_nop 0
	v_fma_f32 v19, -v17, v18, 1.0
	v_fmac_f32_e32 v18, v19, v18
	v_div_scale_f32 v19, vcc, v16, v15, v16
	v_mul_f32_e32 v20, v19, v18
	v_fma_f32 v21, -v17, v20, v19
	v_fmac_f32_e32 v20, v21, v18
	v_fma_f32 v17, -v17, v20, v19
	v_div_fmas_f32 v17, v17, v18, v20
	v_div_fixup_f32 v15, v17, v15, v16
	v_div_scale_f32 v16, s[0:1], v14, v14, v5
	v_rcp_f32_e32 v17, v16
	s_nop 0
	v_fma_f32 v18, -v16, v17, 1.0
	v_fmac_f32_e32 v17, v18, v17
	v_div_scale_f32 v18, vcc, v5, v14, v5
	v_mul_f32_e32 v19, v18, v17
	v_fma_f32 v20, -v16, v19, v18
	v_fmac_f32_e32 v19, v20, v17
	v_fma_f32 v16, -v16, v19, v18
	v_div_fmas_f32 v16, v16, v17, v19
	v_div_fixup_f32 v14, v16, v14, v5
	v_pk_mul_f32 v[14:15], v[8:9], v[14:15]
	v_cvt_pk_bf16_f32 v8, v2, v3
	v_cvt_pk_bf16_f32 v9, v10, v11
	v_cvt_pk_bf16_f32 v10, v12, v13
	v_cvt_pk_bf16_f32 v11, v14, v15
	s_nop 0
	v_permlane32_swap_b32_e32 v8, v10
	v_permlane32_swap_b32_e32 v9, v11
	global_store_dwordx4 v[6:7], v[8:11], off offset:32
	s_waitcnt vmcnt(3)
	v_mov_b32_e32 v5, v70
	s_nop 1
	v_mov_b32_e32 v8, v68
	s_nop 1
	v_permlane32_swap_b32_e32 v8, v5
	v_lshlrev_b32_e32 v12, 16, v8
	v_and_b32_e32 v8, 0xffff0000, v8
	v_mov_b32_e32 v14, v71
	v_mul_f32_e32 v10, 0xbfb8aa3b, v12
	v_mul_f32_e32 v11, 0xbfb8aa3b, v8
	v_exp_f32_e32 v10, v10
	v_exp_f32_e32 v11, v11
	v_mov_b32_e32 v9, v69
	s_nop 1
	v_permlane32_swap_b32_e32 v9, v14
	v_pk_mul_f32 v[2:3], v[32:33], v[4:5] op_sel_hi:[1,0]
	v_pk_add_f32 v[10:11], v[10:11], 1.0 op_sel_hi:[1,0]
	s_nop 0
	v_div_scale_f32 v13, s[0:1], v11, v11, v8
	v_rcp_f32_e32 v15, v13
	s_nop 0
	v_fma_f32 v16, -v13, v15, 1.0
	v_fmac_f32_e32 v15, v16, v15
	v_div_scale_f32 v16, vcc, v8, v11, v8
	v_mul_f32_e32 v17, v16, v15
	v_fma_f32 v18, -v13, v17, v16
	v_fmac_f32_e32 v17, v18, v15
	v_fma_f32 v13, -v13, v17, v16
	v_div_fmas_f32 v13, v13, v15, v17
	v_div_fixup_f32 v11, v13, v11, v8
	v_div_scale_f32 v8, s[0:1], v10, v10, v12
	v_rcp_f32_e32 v13, v8
	s_nop 0
	v_fma_f32 v15, -v8, v13, 1.0
	v_fmac_f32_e32 v13, v15, v13
	v_div_scale_f32 v15, vcc, v12, v10, v12
	v_mul_f32_e32 v16, v15, v13
	v_fma_f32 v17, -v8, v16, v15
	v_fmac_f32_e32 v16, v17, v13
	v_fma_f32 v8, -v8, v16, v15
	v_div_fmas_f32 v8, v8, v13, v16
	v_div_fixup_f32 v10, v8, v10, v12
	v_lshlrev_b32_e32 v12, 16, v9
	v_and_b32_e32 v13, 0xffff0000, v9
	v_pk_mul_f32 v[2:3], v[2:3], v[10:11]
	v_mul_f32_e32 v10, 0xbfb8aa3b, v12
	v_mul_f32_e32 v11, 0xbfb8aa3b, v13
	v_exp_f32_e32 v10, v10
	v_exp_f32_e32 v11, v11
	v_pk_mul_f32 v[8:9], v[34:35], v[4:5] op_sel_hi:[1,0]
	v_pk_add_f32 v[10:11], v[10:11], 1.0 op_sel_hi:[1,0]
	s_nop 0
	v_div_scale_f32 v15, s[0:1], v11, v11, v13
	v_rcp_f32_e32 v16, v15
	s_nop 0
	v_fma_f32 v17, -v15, v16, 1.0
	v_fmac_f32_e32 v16, v17, v16
	v_div_scale_f32 v17, vcc, v13, v11, v13
	v_mul_f32_e32 v18, v17, v16
	v_fma_f32 v19, -v15, v18, v17
	v_fmac_f32_e32 v18, v19, v16
	v_fma_f32 v15, -v15, v18, v17
	v_div_fmas_f32 v15, v15, v16, v18
	v_div_fixup_f32 v11, v15, v11, v13
	v_div_scale_f32 v13, s[0:1], v10, v10, v12
	v_rcp_f32_e32 v15, v13
	s_nop 0
	v_fma_f32 v16, -v13, v15, 1.0
	v_fmac_f32_e32 v15, v16, v15
	v_div_scale_f32 v16, vcc, v12, v10, v12
	v_mul_f32_e32 v17, v16, v15
	v_fma_f32 v18, -v13, v17, v16
	v_fmac_f32_e32 v17, v18, v15
	v_fma_f32 v13, -v13, v17, v16
	v_div_fmas_f32 v13, v13, v15, v17
	v_lshlrev_b32_e32 v15, 16, v5
	v_and_b32_e32 v5, 0xffff0000, v5
	v_div_fixup_f32 v10, v13, v10, v12
	v_mul_f32_e32 v12, 0xbfb8aa3b, v15
	v_mul_f32_e32 v13, 0xbfb8aa3b, v5
	v_exp_f32_e32 v12, v12
	v_exp_f32_e32 v13, v13
	v_pk_mul_f32 v[10:11], v[8:9], v[10:11]
	v_pk_mul_f32 v[8:9], v[36:37], v[4:5] op_sel_hi:[1,0]
	v_pk_add_f32 v[12:13], v[12:13], 1.0 op_sel_hi:[1,0]
	s_nop 0
	v_div_scale_f32 v16, s[0:1], v13, v13, v5
	v_rcp_f32_e32 v17, v16
	s_nop 0
	v_fma_f32 v18, -v16, v17, 1.0
	v_fmac_f32_e32 v17, v18, v17
	v_div_scale_f32 v18, vcc, v5, v13, v5
	v_mul_f32_e32 v19, v18, v17
	v_fma_f32 v20, -v16, v19, v18
	v_fmac_f32_e32 v19, v20, v17
	v_fma_f32 v16, -v16, v19, v18
	v_div_fmas_f32 v16, v16, v17, v19
	v_div_fixup_f32 v13, v16, v13, v5
	v_div_scale_f32 v5, s[0:1], v12, v12, v15
	v_rcp_f32_e32 v16, v5
	s_nop 0
	v_fma_f32 v17, -v5, v16, 1.0
	v_fmac_f32_e32 v16, v17, v16
	v_div_scale_f32 v17, vcc, v15, v12, v15
	v_mul_f32_e32 v18, v17, v16
	v_fma_f32 v19, -v5, v18, v17
	v_fmac_f32_e32 v18, v19, v16
	v_fma_f32 v5, -v5, v18, v17
	v_div_fmas_f32 v5, v5, v16, v18
	v_div_fixup_f32 v12, v5, v12, v15
	v_lshlrev_b32_e32 v5, 16, v14
	v_and_b32_e32 v16, 0xffff0000, v14
	v_mul_f32_e32 v14, 0xbfb8aa3b, v5
	v_mul_f32_e32 v15, 0xbfb8aa3b, v16
	v_exp_f32_e32 v14, v14
	v_exp_f32_e32 v15, v15
	v_pk_mul_f32 v[12:13], v[8:9], v[12:13]
	v_pk_mul_f32 v[8:9], v[38:39], v[4:5] op_sel_hi:[1,0]
	v_pk_add_f32 v[14:15], v[14:15], 1.0 op_sel_hi:[1,0]
	s_nop 0
	v_div_scale_f32 v17, s[0:1], v15, v15, v16
	v_rcp_f32_e32 v18, v17
	s_nop 0
	v_fma_f32 v19, -v17, v18, 1.0
	v_fmac_f32_e32 v18, v19, v18
	v_div_scale_f32 v19, vcc, v16, v15, v16
	v_mul_f32_e32 v20, v19, v18
	v_fma_f32 v21, -v17, v20, v19
	v_fmac_f32_e32 v20, v21, v18
	v_fma_f32 v17, -v17, v20, v19
	v_div_fmas_f32 v17, v17, v18, v20
	v_div_fixup_f32 v15, v17, v15, v16
	v_div_scale_f32 v16, s[0:1], v14, v14, v5
	v_rcp_f32_e32 v17, v16
	s_nop 0
	v_fma_f32 v18, -v16, v17, 1.0
	v_fmac_f32_e32 v17, v18, v17
	v_div_scale_f32 v18, vcc, v5, v14, v5
	v_mul_f32_e32 v19, v18, v17
	v_fma_f32 v20, -v16, v19, v18
	v_fmac_f32_e32 v19, v20, v17
	v_fma_f32 v16, -v16, v19, v18
	v_div_fmas_f32 v16, v16, v17, v19
	v_div_fixup_f32 v14, v16, v14, v5
	v_pk_mul_f32 v[14:15], v[8:9], v[14:15]
	v_cvt_pk_bf16_f32 v8, v2, v3
	v_cvt_pk_bf16_f32 v9, v10, v11
	v_cvt_pk_bf16_f32 v10, v12, v13
	v_cvt_pk_bf16_f32 v11, v14, v15
	s_nop 0
	v_permlane32_swap_b32_e32 v8, v10
	v_permlane32_swap_b32_e32 v9, v11
	global_store_dwordx4 v[6:7], v[8:11], off offset:64
	s_waitcnt vmcnt(3)
	v_mov_b32_e32 v5, v74
	s_nop 1
	v_mov_b32_e32 v0, v72
	s_nop 1
	v_permlane32_swap_b32_e32 v0, v5
	v_lshlrev_b32_e32 v10, 16, v0
	v_and_b32_e32 v0, 0xffff0000, v0
	v_mul_f32_e32 v8, 0xbfb8aa3b, v10
	v_mul_f32_e32 v9, 0xbfb8aa3b, v0
	v_exp_f32_e32 v8, v8
	v_exp_f32_e32 v9, v9
	v_mov_b32_e32 v12, v75
	s_nop 1
	v_mov_b32_e32 v1, v73
	s_nop 1
	v_permlane32_swap_b32_e32 v1, v12
	v_pk_add_f32 v[8:9], v[8:9], 1.0 op_sel_hi:[1,0]
	v_pk_mul_f32 v[2:3], v[40:41], v[4:5] op_sel_hi:[1,0]
	v_div_scale_f32 v11, s[0:1], v9, v9, v0
	v_rcp_f32_e32 v13, v11
	s_nop 0
	v_fma_f32 v14, -v11, v13, 1.0
	v_fmac_f32_e32 v13, v14, v13
	v_div_scale_f32 v14, vcc, v0, v9, v0
	v_mul_f32_e32 v15, v14, v13
	v_fma_f32 v16, -v11, v15, v14
	v_fmac_f32_e32 v15, v16, v13
	v_fma_f32 v11, -v11, v15, v14
	v_div_fmas_f32 v11, v11, v13, v15
	v_div_fixup_f32 v9, v11, v9, v0
	v_div_scale_f32 v0, s[0:1], v8, v8, v10
	v_rcp_f32_e32 v11, v0
	s_nop 0
	v_fma_f32 v13, -v0, v11, 1.0
	v_fmac_f32_e32 v11, v13, v11
	v_div_scale_f32 v13, vcc, v10, v8, v10
	v_mul_f32_e32 v14, v13, v11
	v_fma_f32 v15, -v0, v14, v13
	v_fmac_f32_e32 v14, v15, v11
	v_fma_f32 v0, -v0, v14, v13
	v_div_fmas_f32 v0, v0, v11, v14
	v_div_fixup_f32 v8, v0, v8, v10
	v_lshlrev_b32_e32 v10, 16, v1
	v_and_b32_e32 v11, 0xffff0000, v1
	v_pk_mul_f32 v[2:3], v[2:3], v[8:9]
	v_mul_f32_e32 v8, 0xbfb8aa3b, v10
	v_mul_f32_e32 v9, 0xbfb8aa3b, v11
	v_exp_f32_e32 v8, v8
	v_exp_f32_e32 v9, v9
	v_pk_mul_f32 v[0:1], v[42:43], v[4:5] op_sel_hi:[1,0]
	v_pk_add_f32 v[8:9], v[8:9], 1.0 op_sel_hi:[1,0]
	s_nop 0
	v_div_scale_f32 v13, s[0:1], v9, v9, v11
	v_rcp_f32_e32 v14, v13
	s_nop 0
	v_fma_f32 v15, -v13, v14, 1.0
	v_fmac_f32_e32 v14, v15, v14
	v_div_scale_f32 v15, vcc, v11, v9, v11
	v_mul_f32_e32 v16, v15, v14
	v_fma_f32 v17, -v13, v16, v15
	v_fmac_f32_e32 v16, v17, v14
	v_fma_f32 v13, -v13, v16, v15
	v_div_fmas_f32 v13, v13, v14, v16
	v_div_fixup_f32 v9, v13, v9, v11
	v_div_scale_f32 v11, s[0:1], v8, v8, v10
	v_rcp_f32_e32 v13, v11
	s_nop 0
	v_fma_f32 v14, -v11, v13, 1.0
	v_fmac_f32_e32 v13, v14, v13
	v_div_scale_f32 v14, vcc, v10, v8, v10
	v_mul_f32_e32 v15, v14, v13
	v_fma_f32 v16, -v11, v15, v14
	v_fmac_f32_e32 v15, v16, v13
	v_fma_f32 v11, -v11, v15, v14
	v_div_fmas_f32 v11, v11, v13, v15
	v_lshlrev_b32_e32 v13, 16, v5
	v_and_b32_e32 v5, 0xffff0000, v5
	v_div_fixup_f32 v8, v11, v8, v10
	v_mul_f32_e32 v10, 0xbfb8aa3b, v13
	v_mul_f32_e32 v11, 0xbfb8aa3b, v5
	v_exp_f32_e32 v10, v10
	v_exp_f32_e32 v11, v11
	v_pk_mul_f32 v[8:9], v[0:1], v[8:9]
	v_pk_mul_f32 v[0:1], v[44:45], v[4:5] op_sel_hi:[1,0]
	v_pk_add_f32 v[10:11], v[10:11], 1.0 op_sel_hi:[1,0]
	s_nop 0
	v_div_scale_f32 v14, s[0:1], v11, v11, v5
	v_rcp_f32_e32 v15, v14
	s_nop 0
	v_fma_f32 v16, -v14, v15, 1.0
	v_fmac_f32_e32 v15, v16, v15
	v_div_scale_f32 v16, vcc, v5, v11, v5
	v_mul_f32_e32 v17, v16, v15
	v_fma_f32 v18, -v14, v17, v16
	v_fmac_f32_e32 v17, v18, v15
	v_fma_f32 v14, -v14, v17, v16
	v_div_fmas_f32 v14, v14, v15, v17
	v_div_fixup_f32 v11, v14, v11, v5
	v_div_scale_f32 v5, s[0:1], v10, v10, v13
	v_rcp_f32_e32 v14, v5
	s_nop 0
	v_fma_f32 v15, -v5, v14, 1.0
	v_fmac_f32_e32 v14, v15, v14
	v_div_scale_f32 v15, vcc, v13, v10, v13
	v_mul_f32_e32 v16, v15, v14
	v_fma_f32 v17, -v5, v16, v15
	v_fmac_f32_e32 v16, v17, v14
	v_fma_f32 v5, -v5, v16, v15
	v_div_fmas_f32 v5, v5, v14, v16
	v_div_fixup_f32 v10, v5, v10, v13
	v_lshlrev_b32_e32 v13, 16, v12
	v_and_b32_e32 v12, 0xffff0000, v12
	v_pk_mul_f32 v[10:11], v[0:1], v[10:11]
	v_pk_mul_f32 v[0:1], v[46:47], v[4:5] op_sel_hi:[1,0]
	v_mul_f32_e32 v4, 0xbfb8aa3b, v13
	v_mul_f32_e32 v5, 0xbfb8aa3b, v12
	v_exp_f32_e32 v4, v4
	v_exp_f32_e32 v5, v5
	s_nop 0
	v_pk_add_f32 v[4:5], v[4:5], 1.0 op_sel_hi:[1,0]
	s_nop 0
	v_div_scale_f32 v14, s[0:1], v5, v5, v12
	v_rcp_f32_e32 v15, v14
	s_nop 0
	v_fma_f32 v16, -v14, v15, 1.0
	v_fmac_f32_e32 v15, v16, v15
	v_div_scale_f32 v16, vcc, v12, v5, v12
	v_mul_f32_e32 v17, v16, v15
	v_fma_f32 v18, -v14, v17, v16
	v_fmac_f32_e32 v17, v18, v15
	v_fma_f32 v14, -v14, v17, v16
	v_div_fmas_f32 v14, v14, v15, v17
	v_div_fixup_f32 v5, v14, v5, v12
	v_div_scale_f32 v12, s[0:1], v4, v4, v13
	v_rcp_f32_e32 v14, v12
	s_nop 0
	v_fma_f32 v15, -v12, v14, 1.0
	v_fmac_f32_e32 v14, v15, v14
	v_div_scale_f32 v15, vcc, v13, v4, v13
	v_mul_f32_e32 v16, v15, v14
	v_fma_f32 v17, -v12, v16, v15
	v_fmac_f32_e32 v16, v17, v14
	v_fma_f32 v12, -v12, v16, v15
	v_div_fmas_f32 v12, v12, v14, v16
	v_div_fixup_f32 v4, v12, v4, v13
	v_pk_mul_f32 v[4:5], v[0:1], v[4:5]
	v_cvt_pk_bf16_f32 v0, v2, v3
	v_cvt_pk_bf16_f32 v1, v8, v9
	v_cvt_pk_bf16_f32 v2, v10, v11
	v_cvt_pk_bf16_f32 v3, v4, v5
	s_nop 0
	v_permlane32_swap_b32_e32 v0, v2
	v_permlane32_swap_b32_e32 v1, v3
	global_store_dwordx4 v[6:7], v[0:3], off offset:96
	s_branch .LBB0_476

.LBB0_475:
	v_lshlrev_b32_e32 v0, 16, v199
	v_mul_f32_e32 v0, 0xbfb8aa3b, v0
	v_exp_f32_e32 v0, v0
	v_lshlrev_b64 v[10:11], 11, v[200:201]
	v_lshlrev_b32_e32 v192, 1, v235
	v_readlane_b32 s10, v254, 51
	v_add_f32_e32 v0, 1.0, v0
	v_div_scale_f32 v1, s[0:1], v0, v0, 1.0
	v_rcp_f32_e32 v2, v1
	s_nop 0
	v_fma_f32 v3, -v1, v2, 1.0
	v_fmac_f32_e32 v2, v3, v2
	v_div_scale_f32 v3, vcc, 1.0, v0, 1.0
	v_mul_f32_e32 v4, v3, v2
	v_fma_f32 v5, -v1, v4, v3
	v_fmac_f32_e32 v4, v5, v2
	v_fma_f32 v1, -v1, v4, v3
	v_div_fmas_f32 v1, v1, v2, v4
	v_div_fixup_f32 v4, v1, v0, 1.0
	v_and_b32_e32 v0, 0xffff0000, v199
	v_mul_f32_e32 v0, 0xbfb8aa3b, v0
	v_exp_f32_e32 v206, v0
	s_waitcnt lgkmcnt(0)
	v_pk_add_f32 v[0:1], v[206:207], v[194:195]
	s_nop 0
	v_div_scale_f32 v2, s[0:1], v0, v0, 1.0
	v_rcp_f32_e32 v3, v2
	ds_bpermute_b32 v195, v236, v209
	v_fma_f32 v5, -v2, v3, 1.0
	v_fmac_f32_e32 v3, v5, v3
	v_div_scale_f32 v5, vcc, 1.0, v0, 1.0
	v_mul_f32_e32 v6, v5, v3
	v_fma_f32 v7, -v2, v6, v5
	v_fmac_f32_e32 v6, v7, v3
	v_fma_f32 v2, -v2, v6, v5
	v_div_fmas_f32 v2, v2, v3, v6
	v_div_fixup_f32 v0, v2, v0, 1.0
	v_div_scale_f32 v2, s[0:1], v1, v1, v0
	v_rcp_f32_e32 v3, v2
	s_nop 0
	v_fma_f32 v5, -v2, v3, 1.0
	v_fmac_f32_e32 v3, v5, v3
	v_div_scale_f32 v5, vcc, v0, v1, v0
	v_mul_f32_e32 v6, v5, v3
	v_fma_f32 v7, -v2, v6, v5
	v_fmac_f32_e32 v6, v7, v3
	v_fma_f32 v2, -v2, v6, v5
	v_div_fmas_f32 v2, v2, v3, v6
	v_div_fixup_f32 v6, v2, v1, v0
	v_lshlrev_b32_e32 v0, 16, v197
	v_mul_f32_e32 v0, 0xbfb8aa3b, v0
	v_exp_f32_e32 v208, v0
	s_waitcnt lgkmcnt(0)
	v_pk_add_f32 v[0:1], v[208:209], v[194:195]
	s_nop 0
	v_div_scale_f32 v2, s[0:1], v0, v0, 1.0
	v_rcp_f32_e32 v3, v2
	s_nop 0
	v_fma_f32 v5, -v2, v3, 1.0
	v_fmac_f32_e32 v3, v5, v3
	v_div_scale_f32 v5, vcc, 1.0, v0, 1.0
	v_mul_f32_e32 v7, v5, v3
	v_fma_f32 v8, -v2, v7, v5
	v_fmac_f32_e32 v7, v8, v3
	v_fma_f32 v2, -v2, v7, v5
	v_div_fmas_f32 v2, v2, v3, v7
	v_div_fixup_f32 v0, v2, v0, 1.0
	v_div_scale_f32 v2, s[0:1], v1, v1, v0
	v_rcp_f32_e32 v3, v2
	v_readlane_b32 s0, v254, 43
	v_readlane_b32 s1, v254, 44
	v_fma_f32 v5, -v2, v3, 1.0
	v_fmac_f32_e32 v3, v5, v3
	v_div_scale_f32 v5, vcc, v0, v1, v0
	v_mul_f32_e32 v7, v5, v3
	v_fma_f32 v8, -v2, v7, v5
	v_fmac_f32_e32 v7, v8, v3
	v_fma_f32 v2, -v2, v7, v5
	v_div_fmas_f32 v2, v2, v3, v7
	v_div_fixup_f32 v8, v2, v1, v0
	v_lshlrev_b64 v[0:1], 1, v[204:205]
	v_lshl_add_u64 v[2:3], v[202:203], 0, v[0:1]
	v_lshl_add_u64 v[10:11], s[0:1], 0, v[10:11]
	v_lshl_add_u64 v[10:11], v[10:11], 0, v[0:1]
	v_lshl_add_u64 v[2:3], v[2:3], 0, v[192:193]
	s_mov_b64 s[0:1], 0x1200
	v_lshl_add_u64 v[0:1], v[2:3], 0, s[0:1]
	v_lshl_add_u64 v[16:17], v[10:11], 0, v[192:193]
	s_mov_b64 s[0:1], 0xd210400
	v_lshl_add_u64 v[10:11], v[16:17], 0, s[0:1]
	s_movk_i32 s0, 0x1000
	v_add_co_u32_e32 v2, vcc, s0, v2
	s_nop 1
	v_addc_co_u32_e32 v3, vcc, 0, v3, vcc
	global_load_dwordx4 v[12:15], v[2:3], off offset:512
	global_load_dwordx4 v[128:131], v[0:1], off offset:32
	global_load_dwordx4 v[132:135], v[0:1], off offset:64
	global_load_dwordx4 v[136:139], v[0:1], off offset:96
	v_readlane_b32 s98, v253, 59
	v_readlane_b32 s99, v253, 60
	s_nop 1
	v_writelane_b32 v140, s98, 40
	v_writelane_b32 v141, s99, 40
	s_mov_b64 s[98:99], exec
	v_cmpx_eq_u32_e64 exec, 40, v234
	s_nop 3
	v_writelane_b32 v255, exec_hi, 41
	global_atomic_add v255, v[140:141], v251, off sc0
	s_mov_b64 exec, s[98:99]
	s_waitcnt vmcnt(3)
	v_mov_b32_e32 v5, v14
	s_nop 1
	v_permlane32_swap_b32_e32 v12, v5
	v_lshlrev_b32_e32 v9, 16, v12
	v_and_b32_e32 v12, 0xffff0000, v12
	v_mov_b32_e32 v7, v15
	v_mul_f32_e32 v14, 0xbfb8aa3b, v9
	v_mul_f32_e32 v15, 0xbfb8aa3b, v12
	v_exp_f32_e32 v14, v14
	v_exp_f32_e32 v15, v15
	v_permlane32_swap_b32_e32 v13, v7
	v_pk_mul_f32 v[2:3], v[96:97], v[6:7] op_sel_hi:[1,0]
	v_pk_add_f32 v[14:15], v[14:15], 1.0 op_sel_hi:[1,0]
	v_pk_fma_f32 v[2:3], v[4:5], v[80:81], v[2:3] op_sel_hi:[0,1,1]
	v_div_scale_f32 v18, s[0:1], v15, v15, v12
	v_rcp_f32_e32 v19, v18
	v_pk_fma_f32 v[2:3], v[112:113], v[8:9], v[2:3] op_sel_hi:[1,0,1]
	v_fma_f32 v20, -v18, v19, 1.0
	v_fmac_f32_e32 v19, v20, v19
	v_div_scale_f32 v20, vcc, v12, v15, v12
	v_mul_f32_e32 v21, v20, v19
	v_fma_f32 v22, -v18, v21, v20
	v_fmac_f32_e32 v21, v22, v19
	v_fma_f32 v18, -v18, v21, v20
	v_div_fmas_f32 v18, v18, v19, v21
	v_div_fixup_f32 v15, v18, v15, v12
	v_div_scale_f32 v12, s[0:1], v14, v14, v9
	v_rcp_f32_e32 v18, v12
	s_nop 0
	v_fma_f32 v19, -v12, v18, 1.0
	v_fmac_f32_e32 v18, v19, v18
	v_div_scale_f32 v19, vcc, v9, v14, v9
	v_mul_f32_e32 v20, v19, v18
	v_fma_f32 v21, -v12, v20, v19
	v_fmac_f32_e32 v20, v21, v18
	v_fma_f32 v12, -v12, v20, v19
	v_div_fmas_f32 v12, v12, v18, v20
	v_div_fixup_f32 v14, v12, v14, v9
	v_lshlrev_b32_e32 v9, 16, v13
	v_and_b32_e32 v18, 0xffff0000, v13
	v_pk_mul_f32 v[2:3], v[2:3], v[14:15]
	v_mul_f32_e32 v14, 0xbfb8aa3b, v9
	v_mul_f32_e32 v15, 0xbfb8aa3b, v18
	v_exp_f32_e32 v14, v14
	v_exp_f32_e32 v15, v15
	v_pk_mul_f32 v[12:13], v[98:99], v[6:7] op_sel_hi:[1,0]
	v_pk_add_f32 v[14:15], v[14:15], 1.0 op_sel_hi:[1,0]
	s_nop 0
	v_div_scale_f32 v19, s[0:1], v15, v15, v18
	v_rcp_f32_e32 v20, v19
	v_pk_fma_f32 v[12:13], v[4:5], v[82:83], v[12:13] op_sel_hi:[0,1,1]
	v_pk_fma_f32 v[12:13], v[114:115], v[8:9], v[12:13] op_sel_hi:[1,0,1]
	v_fma_f32 v21, -v19, v20, 1.0
	v_fmac_f32_e32 v20, v21, v20
	v_div_scale_f32 v21, vcc, v18, v15, v18
	v_mul_f32_e32 v22, v21, v20
	v_fma_f32 v23, -v19, v22, v21
	v_fmac_f32_e32 v22, v23, v20
	v_fma_f32 v19, -v19, v22, v21
	v_div_fmas_f32 v19, v19, v20, v22
	v_div_fixup_f32 v15, v19, v15, v18
	v_div_scale_f32 v18, s[0:1], v14, v14, v9
	v_rcp_f32_e32 v19, v18
	s_nop 0
	v_fma_f32 v20, -v18, v19, 1.0
	v_fmac_f32_e32 v19, v20, v19
	v_div_scale_f32 v20, vcc, v9, v14, v9
	v_mul_f32_e32 v21, v20, v19
	v_fma_f32 v22, -v18, v21, v20
	v_fmac_f32_e32 v21, v22, v19
	v_fma_f32 v18, -v18, v21, v20
	v_div_fmas_f32 v18, v18, v19, v21
	v_div_fixup_f32 v14, v18, v14, v9
	v_lshlrev_b32_e32 v9, 16, v5
	v_and_b32_e32 v5, 0xffff0000, v5
	v_mul_f32_e32 v18, 0xbfb8aa3b, v9
	v_mul_f32_e32 v19, 0xbfb8aa3b, v5
	v_exp_f32_e32 v18, v18
	v_exp_f32_e32 v19, v19
	v_pk_mul_f32 v[14:15], v[12:13], v[14:15]
	v_pk_mul_f32 v[12:13], v[100:101], v[6:7] op_sel_hi:[1,0]
	v_pk_add_f32 v[18:19], v[18:19], 1.0 op_sel_hi:[1,0]
	s_nop 0
	v_div_scale_f32 v20, s[0:1], v19, v19, v5
	v_rcp_f32_e32 v21, v20
	v_pk_fma_f32 v[12:13], v[4:5], v[84:85], v[12:13] op_sel_hi:[0,1,1]
	v_pk_fma_f32 v[12:13], v[116:117], v[8:9], v[12:13] op_sel_hi:[1,0,1]
	v_fma_f32 v22, -v20, v21, 1.0
	v_fmac_f32_e32 v21, v22, v21
	v_div_scale_f32 v22, vcc, v5, v19, v5
	v_mul_f32_e32 v23, v22, v21
	v_fma_f32 v24, -v20, v23, v22
	v_fmac_f32_e32 v23, v24, v21
	v_fma_f32 v20, -v20, v23, v22
	v_div_fmas_f32 v20, v20, v21, v23
	v_div_fixup_f32 v19, v20, v19, v5
	v_div_scale_f32 v5, s[0:1], v18, v18, v9
	v_rcp_f32_e32 v20, v5
	s_nop 0
	v_fma_f32 v21, -v5, v20, 1.0
	v_fmac_f32_e32 v20, v21, v20
	v_div_scale_f32 v21, vcc, v9, v18, v9
	v_mul_f32_e32 v22, v21, v20
	v_fma_f32 v23, -v5, v22, v21
	v_fmac_f32_e32 v22, v23, v20
	v_fma_f32 v5, -v5, v22, v21
	v_div_fmas_f32 v5, v5, v20, v22
	v_div_fixup_f32 v18, v5, v18, v9
	v_lshlrev_b32_e32 v5, 16, v7
	v_and_b32_e32 v7, 0xffff0000, v7
	v_pk_mul_f32 v[18:19], v[12:13], v[18:19]
	v_pk_mul_f32 v[12:13], v[102:103], v[6:7] op_sel_hi:[1,0]
	s_nop 0
	v_pk_fma_f32 v[12:13], v[4:5], v[86:87], v[12:13] op_sel_hi:[0,1,1]
	v_pk_fma_f32 v[12:13], v[118:119], v[8:9], v[12:13] op_sel_hi:[1,0,1]
	v_mul_f32_e32 v9, 0xbfb8aa3b, v5
	v_exp_f32_e32 v20, v9
	v_mul_f32_e32 v9, 0xbfb8aa3b, v7
	v_exp_f32_e32 v21, v9
	s_nop 0
	v_pk_add_f32 v[20:21], v[20:21], 1.0 op_sel_hi:[1,0]
	s_nop 0
	v_div_scale_f32 v9, s[0:1], v21, v21, v7
	v_rcp_f32_e32 v22, v9
	s_nop 0
	v_fma_f32 v23, -v9, v22, 1.0
	v_fmac_f32_e32 v22, v23, v22
	v_div_scale_f32 v23, vcc, v7, v21, v7
	v_mul_f32_e32 v24, v23, v22
	v_fma_f32 v25, -v9, v24, v23
	v_fmac_f32_e32 v24, v25, v22
	v_fma_f32 v9, -v9, v24, v23
	v_div_fmas_f32 v9, v9, v22, v24
	v_div_fixup_f32 v21, v9, v21, v7
	v_div_scale_f32 v7, s[0:1], v20, v20, v5
	v_rcp_f32_e32 v9, v7
	s_mov_b32 s0, 0xd210000
	v_fma_f32 v22, -v7, v9, 1.0
	v_fmac_f32_e32 v9, v22, v9
	v_div_scale_f32 v22, vcc, v5, v20, v5
	v_mul_f32_e32 v23, v22, v9
	v_fma_f32 v24, -v7, v23, v22
	v_fmac_f32_e32 v23, v24, v9
	v_fma_f32 v7, -v7, v23, v22
	v_div_fmas_f32 v7, v7, v9, v23
	v_div_fixup_f32 v20, v7, v20, v5
	v_pk_mul_f32 v[20:21], v[12:13], v[20:21]
	v_cvt_pk_bf16_f32 v12, v2, v3
	v_cvt_pk_bf16_f32 v13, v14, v15
	v_cvt_pk_bf16_f32 v14, v18, v19
	v_cvt_pk_bf16_f32 v15, v20, v21
	v_add_co_u32_e32 v2, vcc, s0, v16
	v_permlane32_swap_b32_e32 v12, v14
	v_permlane32_swap_b32_e32 v13, v15
	v_addc_co_u32_e32 v3, vcc, 0, v17, vcc
	global_store_dwordx4 v[2:3], v[12:15], off offset:1024
	s_waitcnt vmcnt(3)
	v_mov_b32_e32 v5, v130
	s_nop 1
	v_mov_b32_e32 v12, v128
	s_nop 1
	v_permlane32_swap_b32_e32 v12, v5
	v_lshlrev_b32_e32 v9, 16, v12
	v_and_b32_e32 v12, 0xffff0000, v12
	v_mov_b32_e32 v7, v131
	v_mul_f32_e32 v14, 0xbfb8aa3b, v9
	v_mul_f32_e32 v15, 0xbfb8aa3b, v12
	v_exp_f32_e32 v14, v14
	v_exp_f32_e32 v15, v15
	v_mov_b32_e32 v13, v129
	s_nop 1
	v_permlane32_swap_b32_e32 v13, v7
	v_pk_mul_f32 v[2:3], v[104:105], v[6:7] op_sel_hi:[1,0]
	v_pk_add_f32 v[14:15], v[14:15], 1.0 op_sel_hi:[1,0]
	v_pk_fma_f32 v[2:3], v[4:5], v[88:89], v[2:3] op_sel_hi:[0,1,1]
	v_div_scale_f32 v16, s[0:1], v15, v15, v12
	v_rcp_f32_e32 v17, v16
	v_pk_fma_f32 v[2:3], v[120:121], v[8:9], v[2:3] op_sel_hi:[1,0,1]
	v_fma_f32 v18, -v16, v17, 1.0
	v_fmac_f32_e32 v17, v18, v17
	v_div_scale_f32 v18, vcc, v12, v15, v12
	v_mul_f32_e32 v19, v18, v17
	v_fma_f32 v20, -v16, v19, v18
	v_fmac_f32_e32 v19, v20, v17
	v_fma_f32 v16, -v16, v19, v18
	v_div_fmas_f32 v16, v16, v17, v19
	v_div_fixup_f32 v15, v16, v15, v12
	v_div_scale_f32 v12, s[0:1], v14, v14, v9
	v_rcp_f32_e32 v16, v12
	s_nop 0
	v_fma_f32 v17, -v12, v16, 1.0
	v_fmac_f32_e32 v16, v17, v16
	v_div_scale_f32 v17, vcc, v9, v14, v9
	v_mul_f32_e32 v18, v17, v16
	v_fma_f32 v19, -v12, v18, v17
	v_fmac_f32_e32 v18, v19, v16
	v_fma_f32 v12, -v12, v18, v17
	v_div_fmas_f32 v12, v12, v16, v18
	v_div_fixup_f32 v14, v12, v14, v9
	v_lshlrev_b32_e32 v9, 16, v13
	v_and_b32_e32 v16, 0xffff0000, v13
	v_pk_mul_f32 v[2:3], v[2:3], v[14:15]
	v_mul_f32_e32 v14, 0xbfb8aa3b, v9
	v_mul_f32_e32 v15, 0xbfb8aa3b, v16
	v_exp_f32_e32 v14, v14
	v_exp_f32_e32 v15, v15
	v_pk_mul_f32 v[12:13], v[106:107], v[6:7] op_sel_hi:[1,0]
	v_pk_add_f32 v[14:15], v[14:15], 1.0 op_sel_hi:[1,0]
	s_nop 0
	v_div_scale_f32 v17, s[0:1], v15, v15, v16
	v_rcp_f32_e32 v18, v17
	v_pk_fma_f32 v[12:13], v[4:5], v[90:91], v[12:13] op_sel_hi:[0,1,1]
	v_pk_fma_f32 v[12:13], v[122:123], v[8:9], v[12:13] op_sel_hi:[1,0,1]
	v_fma_f32 v19, -v17, v18, 1.0
	v_fmac_f32_e32 v18, v19, v18
	v_div_scale_f32 v19, vcc, v16, v15, v16
	v_mul_f32_e32 v20, v19, v18
	v_fma_f32 v21, -v17, v20, v19
	v_fmac_f32_e32 v20, v21, v18
	v_fma_f32 v17, -v17, v20, v19
	v_div_fmas_f32 v17, v17, v18, v20
	v_div_fixup_f32 v15, v17, v15, v16
	v_div_scale_f32 v16, s[0:1], v14, v14, v9
	v_rcp_f32_e32 v17, v16
	s_nop 0
	v_fma_f32 v18, -v16, v17, 1.0
	v_fmac_f32_e32 v17, v18, v17
	v_div_scale_f32 v18, vcc, v9, v14, v9
	v_mul_f32_e32 v19, v18, v17
	v_fma_f32 v20, -v16, v19, v18
	v_fmac_f32_e32 v19, v20, v17
	v_fma_f32 v16, -v16, v19, v18
	v_div_fmas_f32 v16, v16, v17, v19
	v_div_fixup_f32 v14, v16, v14, v9
	v_lshlrev_b32_e32 v9, 16, v5
	v_and_b32_e32 v5, 0xffff0000, v5
	v_mul_f32_e32 v16, 0xbfb8aa3b, v9
	v_mul_f32_e32 v17, 0xbfb8aa3b, v5
	v_exp_f32_e32 v16, v16
	v_exp_f32_e32 v17, v17
	v_pk_mul_f32 v[14:15], v[12:13], v[14:15]
	v_pk_mul_f32 v[12:13], v[108:109], v[6:7] op_sel_hi:[1,0]
	v_pk_add_f32 v[16:17], v[16:17], 1.0 op_sel_hi:[1,0]
	s_nop 0
	v_div_scale_f32 v18, s[0:1], v17, v17, v5
	v_rcp_f32_e32 v19, v18
	v_pk_fma_f32 v[12:13], v[4:5], v[92:93], v[12:13] op_sel_hi:[0,1,1]
	v_pk_fma_f32 v[12:13], v[124:125], v[8:9], v[12:13] op_sel_hi:[1,0,1]
	v_fma_f32 v20, -v18, v19, 1.0
	v_fmac_f32_e32 v19, v20, v19
	v_div_scale_f32 v20, vcc, v5, v17, v5
	v_mul_f32_e32 v21, v20, v19
	v_fma_f32 v22, -v18, v21, v20
	v_fmac_f32_e32 v21, v22, v19
	v_fma_f32 v18, -v18, v21, v20
	v_div_fmas_f32 v18, v18, v19, v21
	v_div_fixup_f32 v17, v18, v17, v5
	v_div_scale_f32 v5, s[0:1], v16, v16, v9
	v_rcp_f32_e32 v18, v5
	s_nop 0
	v_fma_f32 v19, -v5, v18, 1.0
	v_fmac_f32_e32 v18, v19, v18
	v_div_scale_f32 v19, vcc, v9, v16, v9
	v_mul_f32_e32 v20, v19, v18
	v_fma_f32 v21, -v5, v20, v19
	v_fmac_f32_e32 v20, v21, v18
	v_fma_f32 v5, -v5, v20, v19
	v_div_fmas_f32 v5, v5, v18, v20
	v_div_fixup_f32 v16, v5, v16, v9
	v_lshlrev_b32_e32 v5, 16, v7
	v_and_b32_e32 v7, 0xffff0000, v7
	v_pk_mul_f32 v[16:17], v[12:13], v[16:17]
	v_pk_mul_f32 v[12:13], v[110:111], v[6:7] op_sel_hi:[1,0]
	s_nop 0
	v_pk_fma_f32 v[12:13], v[4:5], v[94:95], v[12:13] op_sel_hi:[0,1,1]
	v_pk_fma_f32 v[12:13], v[126:127], v[8:9], v[12:13] op_sel_hi:[1,0,1]
	v_mul_f32_e32 v9, 0xbfb8aa3b, v5
	v_exp_f32_e32 v18, v9
	v_mul_f32_e32 v9, 0xbfb8aa3b, v7
	v_exp_f32_e32 v19, v9
	s_nop 0
	v_pk_add_f32 v[18:19], v[18:19], 1.0 op_sel_hi:[1,0]
	s_nop 0
	v_div_scale_f32 v9, s[0:1], v19, v19, v7
	v_rcp_f32_e32 v20, v9
	s_nop 0
	v_fma_f32 v21, -v9, v20, 1.0
	v_fmac_f32_e32 v20, v21, v20
	v_div_scale_f32 v21, vcc, v7, v19, v7
	v_mul_f32_e32 v22, v21, v20
	v_fma_f32 v23, -v9, v22, v21
	v_fmac_f32_e32 v22, v23, v20
	v_fma_f32 v9, -v9, v22, v21
	v_div_fmas_f32 v9, v9, v20, v22
	v_div_fixup_f32 v19, v9, v19, v7
	v_div_scale_f32 v7, s[0:1], v18, v18, v5
	v_rcp_f32_e32 v9, v7
	s_nop 0
	v_fma_f32 v20, -v7, v9, 1.0
	v_fmac_f32_e32 v9, v20, v9
	v_div_scale_f32 v20, vcc, v5, v18, v5
	v_mul_f32_e32 v21, v20, v9
	v_fma_f32 v22, -v7, v21, v20
	v_fmac_f32_e32 v21, v22, v9
	v_fma_f32 v7, -v7, v21, v20
	v_div_fmas_f32 v7, v7, v9, v21
	v_div_fixup_f32 v18, v7, v18, v5
	v_pk_mul_f32 v[18:19], v[12:13], v[18:19]
	v_cvt_pk_bf16_f32 v12, v2, v3
	v_cvt_pk_bf16_f32 v13, v14, v15
	v_cvt_pk_bf16_f32 v14, v16, v17
	v_cvt_pk_bf16_f32 v15, v18, v19
	s_nop 0
	v_permlane32_swap_b32_e32 v12, v14
	v_permlane32_swap_b32_e32 v13, v15
	global_store_dwordx4 v[10:11], v[12:15], off offset:32
	s_waitcnt vmcnt(3)
	v_mov_b32_e32 v5, v134
	s_nop 1
	v_mov_b32_e32 v12, v132
	s_nop 1
	v_permlane32_swap_b32_e32 v12, v5
	v_lshlrev_b32_e32 v9, 16, v12
	v_and_b32_e32 v12, 0xffff0000, v12
	v_mov_b32_e32 v7, v135
	v_mul_f32_e32 v14, 0xbfb8aa3b, v9
	v_mul_f32_e32 v15, 0xbfb8aa3b, v12
	v_exp_f32_e32 v14, v14
	v_exp_f32_e32 v15, v15
	v_mov_b32_e32 v13, v133
	s_nop 1
	v_permlane32_swap_b32_e32 v13, v7
	v_pk_mul_f32 v[2:3], v[48:49], v[6:7] op_sel_hi:[1,0]
	v_pk_add_f32 v[14:15], v[14:15], 1.0 op_sel_hi:[1,0]
	v_pk_fma_f32 v[2:3], v[4:5], v[32:33], v[2:3] op_sel_hi:[0,1,1]
	v_div_scale_f32 v16, s[0:1], v15, v15, v12
	v_rcp_f32_e32 v17, v16
	v_pk_fma_f32 v[2:3], v[64:65], v[8:9], v[2:3] op_sel_hi:[1,0,1]
	v_fma_f32 v18, -v16, v17, 1.0
	v_fmac_f32_e32 v17, v18, v17
	v_div_scale_f32 v18, vcc, v12, v15, v12
	v_mul_f32_e32 v19, v18, v17
	v_fma_f32 v20, -v16, v19, v18
	v_fmac_f32_e32 v19, v20, v17
	v_fma_f32 v16, -v16, v19, v18
	v_div_fmas_f32 v16, v16, v17, v19
	v_div_fixup_f32 v15, v16, v15, v12
	v_div_scale_f32 v12, s[0:1], v14, v14, v9
	v_rcp_f32_e32 v16, v12
	s_nop 0
	v_fma_f32 v17, -v12, v16, 1.0
	v_fmac_f32_e32 v16, v17, v16
	v_div_scale_f32 v17, vcc, v9, v14, v9
	v_mul_f32_e32 v18, v17, v16
	v_fma_f32 v19, -v12, v18, v17
	v_fmac_f32_e32 v18, v19, v16
	v_fma_f32 v12, -v12, v18, v17
	v_div_fmas_f32 v12, v12, v16, v18
	v_div_fixup_f32 v14, v12, v14, v9
	v_lshlrev_b32_e32 v9, 16, v13
	v_and_b32_e32 v16, 0xffff0000, v13
	v_pk_mul_f32 v[2:3], v[2:3], v[14:15]
	v_mul_f32_e32 v14, 0xbfb8aa3b, v9
	v_mul_f32_e32 v15, 0xbfb8aa3b, v16
	v_exp_f32_e32 v14, v14
	v_exp_f32_e32 v15, v15
	v_pk_mul_f32 v[12:13], v[50:51], v[6:7] op_sel_hi:[1,0]
	v_pk_add_f32 v[14:15], v[14:15], 1.0 op_sel_hi:[1,0]
	s_nop 0
	v_div_scale_f32 v17, s[0:1], v15, v15, v16
	v_rcp_f32_e32 v18, v17
	v_pk_fma_f32 v[12:13], v[4:5], v[34:35], v[12:13] op_sel_hi:[0,1,1]
	v_pk_fma_f32 v[12:13], v[66:67], v[8:9], v[12:13] op_sel_hi:[1,0,1]
	v_fma_f32 v19, -v17, v18, 1.0
	v_fmac_f32_e32 v18, v19, v18
	v_div_scale_f32 v19, vcc, v16, v15, v16
	v_mul_f32_e32 v20, v19, v18
	v_fma_f32 v21, -v17, v20, v19
	v_fmac_f32_e32 v20, v21, v18
	v_fma_f32 v17, -v17, v20, v19
	v_div_fmas_f32 v17, v17, v18, v20
	v_div_fixup_f32 v15, v17, v15, v16
	v_div_scale_f32 v16, s[0:1], v14, v14, v9
	v_rcp_f32_e32 v17, v16
	s_nop 0
	v_fma_f32 v18, -v16, v17, 1.0
	v_fmac_f32_e32 v17, v18, v17
	v_div_scale_f32 v18, vcc, v9, v14, v9
	v_mul_f32_e32 v19, v18, v17
	v_fma_f32 v20, -v16, v19, v18
	v_fmac_f32_e32 v19, v20, v17
	v_fma_f32 v16, -v16, v19, v18
	v_div_fmas_f32 v16, v16, v17, v19
	v_div_fixup_f32 v14, v16, v14, v9
	v_lshlrev_b32_e32 v9, 16, v5
	v_and_b32_e32 v5, 0xffff0000, v5
	v_mul_f32_e32 v16, 0xbfb8aa3b, v9
	v_mul_f32_e32 v17, 0xbfb8aa3b, v5
	v_exp_f32_e32 v16, v16
	v_exp_f32_e32 v17, v17
	v_pk_mul_f32 v[14:15], v[12:13], v[14:15]
	v_pk_mul_f32 v[12:13], v[52:53], v[6:7] op_sel_hi:[1,0]
	v_pk_add_f32 v[16:17], v[16:17], 1.0 op_sel_hi:[1,0]
	s_nop 0
	v_div_scale_f32 v18, s[0:1], v17, v17, v5
	v_rcp_f32_e32 v19, v18
	v_pk_fma_f32 v[12:13], v[4:5], v[36:37], v[12:13] op_sel_hi:[0,1,1]
	v_pk_fma_f32 v[12:13], v[68:69], v[8:9], v[12:13] op_sel_hi:[1,0,1]
	v_fma_f32 v20, -v18, v19, 1.0
	v_fmac_f32_e32 v19, v20, v19
	v_div_scale_f32 v20, vcc, v5, v17, v5
	v_mul_f32_e32 v21, v20, v19
	v_fma_f32 v22, -v18, v21, v20
	v_fmac_f32_e32 v21, v22, v19
	v_fma_f32 v18, -v18, v21, v20
	v_div_fmas_f32 v18, v18, v19, v21
	v_div_fixup_f32 v17, v18, v17, v5
	v_div_scale_f32 v5, s[0:1], v16, v16, v9
	v_rcp_f32_e32 v18, v5
	s_nop 0
	v_fma_f32 v19, -v5, v18, 1.0
	v_fmac_f32_e32 v18, v19, v18
	v_div_scale_f32 v19, vcc, v9, v16, v9
	v_mul_f32_e32 v20, v19, v18
	v_fma_f32 v21, -v5, v20, v19
	v_fmac_f32_e32 v20, v21, v18
	v_fma_f32 v5, -v5, v20, v19
	v_div_fmas_f32 v5, v5, v18, v20
	v_div_fixup_f32 v16, v5, v16, v9
	v_lshlrev_b32_e32 v5, 16, v7
	v_and_b32_e32 v7, 0xffff0000, v7
	v_pk_mul_f32 v[16:17], v[12:13], v[16:17]
	v_pk_mul_f32 v[12:13], v[54:55], v[6:7] op_sel_hi:[1,0]
	s_nop 0
	v_pk_fma_f32 v[12:13], v[4:5], v[38:39], v[12:13] op_sel_hi:[0,1,1]
	v_pk_fma_f32 v[12:13], v[70:71], v[8:9], v[12:13] op_sel_hi:[1,0,1]
	v_mul_f32_e32 v9, 0xbfb8aa3b, v5
	v_exp_f32_e32 v18, v9
	v_mul_f32_e32 v9, 0xbfb8aa3b, v7
	v_exp_f32_e32 v19, v9
	s_nop 0
	v_pk_add_f32 v[18:19], v[18:19], 1.0 op_sel_hi:[1,0]
	s_nop 0
	v_div_scale_f32 v9, s[0:1], v19, v19, v7
	v_rcp_f32_e32 v20, v9
	s_nop 0
	v_fma_f32 v21, -v9, v20, 1.0
	v_fmac_f32_e32 v20, v21, v20
	v_div_scale_f32 v21, vcc, v7, v19, v7
	v_mul_f32_e32 v22, v21, v20
	v_fma_f32 v23, -v9, v22, v21
	v_fmac_f32_e32 v22, v23, v20
	v_fma_f32 v9, -v9, v22, v21
	v_div_fmas_f32 v9, v9, v20, v22
	v_div_fixup_f32 v19, v9, v19, v7
	v_div_scale_f32 v7, s[0:1], v18, v18, v5
	v_rcp_f32_e32 v9, v7
	s_nop 0
	v_fma_f32 v20, -v7, v9, 1.0
	v_fmac_f32_e32 v9, v20, v9
	v_div_scale_f32 v20, vcc, v5, v18, v5
	v_mul_f32_e32 v21, v20, v9
	v_fma_f32 v22, -v7, v21, v20
	v_fmac_f32_e32 v21, v22, v9
	v_fma_f32 v7, -v7, v21, v20
	v_div_fmas_f32 v7, v7, v9, v21
	v_div_fixup_f32 v18, v7, v18, v5
	v_pk_mul_f32 v[18:19], v[12:13], v[18:19]
	v_cvt_pk_bf16_f32 v12, v2, v3
	v_cvt_pk_bf16_f32 v13, v14, v15
	v_cvt_pk_bf16_f32 v14, v16, v17
	v_cvt_pk_bf16_f32 v15, v18, v19
	s_nop 0
	v_permlane32_swap_b32_e32 v12, v14
	v_permlane32_swap_b32_e32 v13, v15
	global_store_dwordx4 v[10:11], v[12:15], off offset:64
	s_waitcnt vmcnt(3)
	v_mov_b32_e32 v5, v138
	s_nop 1
	v_mov_b32_e32 v0, v136
	s_nop 1
	v_permlane32_swap_b32_e32 v0, v5
	v_lshlrev_b32_e32 v9, 16, v0
	v_and_b32_e32 v0, 0xffff0000, v0
	v_mul_f32_e32 v12, 0xbfb8aa3b, v9
	v_mul_f32_e32 v13, 0xbfb8aa3b, v0
	v_exp_f32_e32 v12, v12
	v_exp_f32_e32 v13, v13
	v_mov_b32_e32 v7, v139
	s_nop 1
	v_mov_b32_e32 v1, v137
	s_nop 1
	v_permlane32_swap_b32_e32 v1, v7
	v_pk_add_f32 v[12:13], v[12:13], 1.0 op_sel_hi:[1,0]
	v_pk_mul_f32 v[2:3], v[56:57], v[6:7] op_sel_hi:[1,0]
	v_div_scale_f32 v14, s[0:1], v13, v13, v0
	v_rcp_f32_e32 v15, v14
	v_pk_fma_f32 v[2:3], v[4:5], v[40:41], v[2:3] op_sel_hi:[0,1,1]
	v_pk_fma_f32 v[2:3], v[72:73], v[8:9], v[2:3] op_sel_hi:[1,0,1]
	v_fma_f32 v16, -v14, v15, 1.0
	v_fmac_f32_e32 v15, v16, v15
	v_div_scale_f32 v16, vcc, v0, v13, v0
	v_mul_f32_e32 v17, v16, v15
	v_fma_f32 v18, -v14, v17, v16
	v_fmac_f32_e32 v17, v18, v15
	v_fma_f32 v14, -v14, v17, v16
	v_div_fmas_f32 v14, v14, v15, v17
	v_div_fixup_f32 v13, v14, v13, v0
	v_div_scale_f32 v0, s[0:1], v12, v12, v9
	v_rcp_f32_e32 v14, v0
	s_nop 0
	v_fma_f32 v15, -v0, v14, 1.0
	v_fmac_f32_e32 v14, v15, v14
	v_div_scale_f32 v15, vcc, v9, v12, v9
	v_mul_f32_e32 v16, v15, v14
	v_fma_f32 v17, -v0, v16, v15
	v_fmac_f32_e32 v16, v17, v14
	v_fma_f32 v0, -v0, v16, v15
	v_div_fmas_f32 v0, v0, v14, v16
	v_div_fixup_f32 v12, v0, v12, v9
	v_lshlrev_b32_e32 v9, 16, v1
	v_and_b32_e32 v14, 0xffff0000, v1
	v_pk_mul_f32 v[2:3], v[2:3], v[12:13]
	v_mul_f32_e32 v12, 0xbfb8aa3b, v9
	v_mul_f32_e32 v13, 0xbfb8aa3b, v14
	v_exp_f32_e32 v12, v12
	v_exp_f32_e32 v13, v13
	v_pk_mul_f32 v[0:1], v[58:59], v[6:7] op_sel_hi:[1,0]
	v_cvt_pk_bf16_f32 v2, v2, v3
	v_pk_fma_f32 v[0:1], v[4:5], v[42:43], v[0:1] op_sel_hi:[0,1,1]
	v_pk_add_f32 v[12:13], v[12:13], 1.0 op_sel_hi:[1,0]
	v_pk_fma_f32 v[0:1], v[74:75], v[8:9], v[0:1] op_sel_hi:[1,0,1]
	v_div_scale_f32 v15, s[0:1], v13, v13, v14
	v_rcp_f32_e32 v16, v15
	s_nop 0
	v_fma_f32 v17, -v15, v16, 1.0
	v_fmac_f32_e32 v16, v17, v16
	v_div_scale_f32 v17, vcc, v14, v13, v14
	v_mul_f32_e32 v18, v17, v16
	v_fma_f32 v19, -v15, v18, v17
	v_fmac_f32_e32 v18, v19, v16
	v_fma_f32 v15, -v15, v18, v17
	v_div_fmas_f32 v15, v15, v16, v18
	v_div_fixup_f32 v13, v15, v13, v14
	v_div_scale_f32 v14, s[0:1], v12, v12, v9
	v_rcp_f32_e32 v15, v14
	s_nop 0
	v_fma_f32 v16, -v14, v15, 1.0
	v_fmac_f32_e32 v15, v16, v15
	v_div_scale_f32 v16, vcc, v9, v12, v9
	v_mul_f32_e32 v17, v16, v15
	v_fma_f32 v18, -v14, v17, v16
	v_fmac_f32_e32 v17, v18, v15
	v_fma_f32 v14, -v14, v17, v16
	v_div_fmas_f32 v14, v14, v15, v17
	v_div_fixup_f32 v12, v14, v12, v9
	v_lshlrev_b32_e32 v9, 16, v5
	v_and_b32_e32 v5, 0xffff0000, v5
	v_mul_f32_e32 v14, 0xbfb8aa3b, v9
	v_mul_f32_e32 v15, 0xbfb8aa3b, v5
	v_exp_f32_e32 v14, v14
	v_exp_f32_e32 v15, v15
	v_pk_mul_f32 v[0:1], v[0:1], v[12:13]
	v_pk_mul_f32 v[12:13], v[60:61], v[6:7] op_sel_hi:[1,0]
	v_cvt_pk_bf16_f32 v3, v0, v1
	v_pk_add_f32 v[14:15], v[14:15], 1.0 op_sel_hi:[1,0]
	v_pk_fma_f32 v[12:13], v[4:5], v[44:45], v[12:13] op_sel_hi:[0,1,1]
	v_div_scale_f32 v16, s[0:1], v15, v15, v5
	v_rcp_f32_e32 v17, v16
	v_pk_fma_f32 v[12:13], v[76:77], v[8:9], v[12:13] op_sel_hi:[1,0,1]
	v_fma_f32 v18, -v16, v17, 1.0
	v_fmac_f32_e32 v17, v18, v17
	v_div_scale_f32 v18, vcc, v5, v15, v5
	v_mul_f32_e32 v19, v18, v17
	v_fma_f32 v20, -v16, v19, v18
	v_fmac_f32_e32 v19, v20, v17
	v_fma_f32 v16, -v16, v19, v18
	v_div_fmas_f32 v16, v16, v17, v19
	v_div_fixup_f32 v15, v16, v15, v5
	v_div_scale_f32 v5, s[0:1], v14, v14, v9
	v_rcp_f32_e32 v16, v5
	s_nop 0
	v_fma_f32 v17, -v5, v16, 1.0
	v_fmac_f32_e32 v16, v17, v16
	v_div_scale_f32 v17, vcc, v9, v14, v9
	v_mul_f32_e32 v18, v17, v16
	v_fma_f32 v19, -v5, v18, v17
	v_fmac_f32_e32 v18, v19, v16
	v_fma_f32 v5, -v5, v18, v17
	v_div_fmas_f32 v5, v5, v16, v18
	v_div_fixup_f32 v14, v5, v14, v9
	v_pk_mul_f32 v[12:13], v[12:13], v[14:15]
	v_lshlrev_b32_e32 v9, 16, v7
	v_and_b32_e32 v14, 0xffff0000, v7
	v_pk_mul_f32 v[6:7], v[62:63], v[6:7] op_sel_hi:[1,0]
	s_nop 0
	v_pk_fma_f32 v[4:5], v[4:5], v[46:47], v[6:7] op_sel_hi:[0,1,1]
	v_mul_f32_e32 v6, 0xbfb8aa3b, v9
	v_mul_f32_e32 v7, 0xbfb8aa3b, v14
	v_exp_f32_e32 v6, v6
	v_exp_f32_e32 v7, v7
	v_pk_fma_f32 v[4:5], v[78:79], v[8:9], v[4:5] op_sel_hi:[1,0,1]
	v_pk_add_f32 v[6:7], v[6:7], 1.0 op_sel_hi:[1,0]
	s_nop 0
	v_div_scale_f32 v8, s[0:1], v7, v7, v14
	v_rcp_f32_e32 v15, v8
	s_nop 0
	v_fma_f32 v16, -v8, v15, 1.0
	v_fmac_f32_e32 v15, v16, v15
	v_div_scale_f32 v16, vcc, v14, v7, v14
	v_mul_f32_e32 v17, v16, v15
	v_fma_f32 v18, -v8, v17, v16
	v_fmac_f32_e32 v17, v18, v15
	v_fma_f32 v8, -v8, v17, v16
	v_div_fmas_f32 v8, v8, v15, v17
	v_div_fixup_f32 v7, v8, v7, v14
	v_div_scale_f32 v8, s[0:1], v6, v6, v9
	v_rcp_f32_e32 v14, v8
	s_nop 0
	v_fma_f32 v15, -v8, v14, 1.0
	v_fmac_f32_e32 v14, v15, v14
	v_div_scale_f32 v15, vcc, v9, v6, v9
	v_mul_f32_e32 v16, v15, v14
	v_fma_f32 v17, -v8, v16, v15
	v_fmac_f32_e32 v16, v17, v14
	v_fma_f32 v8, -v8, v16, v15
	v_div_fmas_f32 v8, v8, v14, v16
	v_div_fixup_f32 v6, v8, v6, v9
	v_pk_mul_f32 v[6:7], v[4:5], v[6:7]
	v_cvt_pk_bf16_f32 v4, v12, v13
	v_cvt_pk_bf16_f32 v5, v6, v7
	s_nop 0
	v_permlane32_swap_b32_e32 v2, v4
	v_permlane32_swap_b32_e32 v3, v5
	global_store_dwordx4 v[10:11], v[2:5], off offset:96

.LBB0_513:
	s_mov_b64 s[8:9], 0x3e38aa3b
	s_lshl_b32 s0, s1, 1
	s_mov_b32 s1, s9
	v_readlane_b32 s8, v254, 43
	v_lshlrev_b64 v[2:3], 11, v[130:131]
	v_readlane_b32 s9, v254, 44
	v_lshl_add_u64 v[0:1], v[132:133], 0, s[0:1]
	v_mov_b32_e32 v129, v193
	v_lshl_add_u64 v[2:3], s[8:9], 0, v[2:3]
	v_lshl_add_u64 v[2:3], v[2:3], 0, s[0:1]
	v_lshl_add_u64 v[6:7], v[0:1], 0, v[128:129]
	s_mov_b64 s[0:1], 0x1a00
	v_lshl_add_u64 v[0:1], v[6:7], 0, s[0:1]
	v_add_co_u32_e32 v6, vcc, 0x1000, v6
	v_lshl_add_u64 v[2:3], v[2:3], 0, v[128:129]
	s_nop 0
	v_addc_co_u32_e32 v7, vcc, 0, v7, vcc
	global_load_dwordx4 v[6:9], v[6:7], off offset:2560
	global_load_dwordx4 v[64:67], v[0:1], off offset:32
	global_load_dwordx4 v[68:71], v[0:1], off offset:64
	global_load_dwordx4 v[72:75], v[0:1], off offset:96
	v_readlane_b32 s98, v253, 59
	v_readlane_b32 s99, v253, 60
	s_nop 1
	v_writelane_b32 v76, s98, 40
	v_writelane_b32 v77, s99, 40
	s_mov_b64 s[98:99], exec
	v_cmpx_eq_u32_e64 exec, 40, v234
	s_nop 3
	v_writelane_b32 v255, exec_hi, 41
	global_atomic_add v255, v[76:77], v251, off sc0
	s_mov_b64 exec, s[98:99]
	s_mov_b64 s[0:1], 0xd210600
	v_lshl_add_u64 v[4:5], v[2:3], 0, s[0:1]
	v_readlane_b32 s76, v254, 37
	v_readlane_b32 s77, v254, 38
	s_mov_b64 s[8:9], 0
	s_waitcnt vmcnt(3) lgkmcnt(0)
	v_mov_b32_e32 v12, v8
	s_nop 1
	v_permlane32_swap_b32_e32 v6, v12
	v_lshlrev_b32_e32 v10, 16, v6
	v_and_b32_e32 v6, 0xffff0000, v6
	v_mov_b32_e32 v14, v9
	v_mul_f32_e32 v8, 0xbfb8aa3b, v10
	v_mul_f32_e32 v9, 0xbfb8aa3b, v6
	v_exp_f32_e32 v8, v8
	v_exp_f32_e32 v9, v9
	v_permlane32_swap_b32_e32 v7, v14
	v_pk_add_f32 v[8:9], v[8:9], 1.0 op_sel_hi:[1,0]
	s_nop 0
	v_div_scale_f32 v11, s[0:1], v9, v9, v6
	v_rcp_f32_e32 v13, v11
	s_nop 0
	v_fma_f32 v15, -v11, v13, 1.0
	v_fmac_f32_e32 v13, v15, v13
	v_div_scale_f32 v15, vcc, v6, v9, v6
	v_mul_f32_e32 v16, v15, v13
	v_fma_f32 v17, -v11, v16, v15
	v_fmac_f32_e32 v16, v17, v13
	v_fma_f32 v11, -v11, v16, v15
	v_div_fmas_f32 v11, v11, v13, v16
	v_div_fixup_f32 v9, v11, v9, v6
	v_div_scale_f32 v6, s[0:1], v8, v8, v10
	v_rcp_f32_e32 v11, v6
	s_nop 0
	v_fma_f32 v13, -v6, v11, 1.0
	v_fmac_f32_e32 v11, v13, v11
	v_div_scale_f32 v13, vcc, v10, v8, v10
	v_mul_f32_e32 v15, v13, v11
	v_fma_f32 v16, -v6, v15, v13
	v_fmac_f32_e32 v15, v16, v11
	v_fma_f32 v6, -v6, v15, v13
	v_div_fmas_f32 v6, v6, v11, v15
	v_div_fixup_f32 v8, v6, v8, v10
	v_lshlrev_b32_e32 v10, 16, v7
	v_and_b32_e32 v11, 0xffff0000, v7
	v_mul_f32_e32 v6, 0xbfb8aa3b, v10
	v_mul_f32_e32 v7, 0xbfb8aa3b, v11
	v_exp_f32_e32 v6, v6
	v_exp_f32_e32 v7, v7
	v_pk_mul_f32 v[8:9], v[48:49], v[8:9]
	v_pk_add_f32 v[6:7], v[6:7], 1.0 op_sel_hi:[1,0]
	s_nop 0
	v_div_scale_f32 v13, s[0:1], v7, v7, v11
	v_rcp_f32_e32 v15, v13
	s_nop 0
	v_fma_f32 v16, -v13, v15, 1.0
	v_fmac_f32_e32 v15, v16, v15
	v_div_scale_f32 v16, vcc, v11, v7, v11
	v_mul_f32_e32 v17, v16, v15
	v_fma_f32 v18, -v13, v17, v16
	v_fmac_f32_e32 v17, v18, v15
	v_fma_f32 v13, -v13, v17, v16
	v_div_fmas_f32 v13, v13, v15, v17
	v_div_fixup_f32 v7, v13, v7, v11
	v_div_scale_f32 v11, s[0:1], v6, v6, v10
	v_rcp_f32_e32 v13, v11
	s_nop 0
	v_fma_f32 v15, -v11, v13, 1.0
	v_fmac_f32_e32 v13, v15, v13
	v_div_scale_f32 v15, vcc, v10, v6, v10
	v_mul_f32_e32 v16, v15, v13
	v_fma_f32 v17, -v11, v16, v15
	v_fmac_f32_e32 v16, v17, v13
	v_fma_f32 v11, -v11, v16, v15
	v_div_fmas_f32 v11, v11, v13, v16
	v_div_fixup_f32 v6, v11, v6, v10
	v_lshlrev_b32_e32 v13, 16, v12
	v_and_b32_e32 v12, 0xffff0000, v12
	v_pk_mul_f32 v[10:11], v[50:51], v[6:7]
	v_mul_f32_e32 v6, 0xbfb8aa3b, v13
	v_mul_f32_e32 v7, 0xbfb8aa3b, v12
	v_exp_f32_e32 v6, v6
	v_exp_f32_e32 v7, v7
	s_nop 0
	v_pk_add_f32 v[6:7], v[6:7], 1.0 op_sel_hi:[1,0]
	s_nop 0
	v_div_scale_f32 v15, s[0:1], v7, v7, v12
	v_rcp_f32_e32 v16, v15
	s_nop 0
	v_fma_f32 v17, -v15, v16, 1.0
	v_fmac_f32_e32 v16, v17, v16
	v_div_scale_f32 v17, vcc, v12, v7, v12
	v_mul_f32_e32 v18, v17, v16
	v_fma_f32 v19, -v15, v18, v17
	v_fmac_f32_e32 v18, v19, v16
	v_fma_f32 v15, -v15, v18, v17
	v_div_fmas_f32 v15, v15, v16, v18
	v_div_fixup_f32 v7, v15, v7, v12
	v_div_scale_f32 v12, s[0:1], v6, v6, v13
	v_rcp_f32_e32 v15, v12
	s_nop 0
	v_fma_f32 v16, -v12, v15, 1.0
	v_fmac_f32_e32 v15, v16, v15
	v_div_scale_f32 v16, vcc, v13, v6, v13
	v_mul_f32_e32 v17, v16, v15
	v_fma_f32 v18, -v12, v17, v16
	v_fmac_f32_e32 v17, v18, v15
	v_fma_f32 v12, -v12, v17, v16
	v_div_fmas_f32 v12, v12, v15, v17
	v_div_fixup_f32 v6, v12, v6, v13
	v_lshlrev_b32_e32 v15, 16, v14
	v_and_b32_e32 v14, 0xffff0000, v14
	v_pk_mul_f32 v[12:13], v[52:53], v[6:7]
	v_mul_f32_e32 v6, 0xbfb8aa3b, v15
	v_mul_f32_e32 v7, 0xbfb8aa3b, v14
	v_exp_f32_e32 v6, v6
	v_exp_f32_e32 v7, v7
	s_nop 0
	v_pk_add_f32 v[6:7], v[6:7], 1.0 op_sel_hi:[1,0]
	s_nop 0
	v_div_scale_f32 v16, s[0:1], v7, v7, v14
	v_rcp_f32_e32 v17, v16
	s_nop 0
	v_fma_f32 v18, -v16, v17, 1.0
	v_fmac_f32_e32 v17, v18, v17
	v_div_scale_f32 v18, vcc, v14, v7, v14
	v_mul_f32_e32 v19, v18, v17
	v_fma_f32 v20, -v16, v19, v18
	v_fmac_f32_e32 v19, v20, v17
	v_fma_f32 v16, -v16, v19, v18
	v_div_fmas_f32 v16, v16, v17, v19
	v_div_fixup_f32 v7, v16, v7, v14
	v_div_scale_f32 v14, s[0:1], v6, v6, v15
	v_rcp_f32_e32 v16, v14
	s_mov_b32 s0, 0xd210000
	v_fma_f32 v17, -v14, v16, 1.0
	v_fmac_f32_e32 v16, v17, v16
	v_div_scale_f32 v17, vcc, v15, v6, v15
	v_mul_f32_e32 v18, v17, v16
	v_fma_f32 v19, -v14, v18, v17
	v_fmac_f32_e32 v18, v19, v16
	v_fma_f32 v14, -v14, v18, v17
	v_div_fmas_f32 v14, v14, v16, v18
	v_div_fixup_f32 v6, v14, v6, v15
	v_pk_mul_f32 v[14:15], v[54:55], v[6:7]
	v_cvt_pk_bf16_f32 v6, v8, v9
	v_cvt_pk_bf16_f32 v7, v10, v11
	v_cvt_pk_bf16_f32 v8, v12, v13
	v_cvt_pk_bf16_f32 v9, v14, v15
	v_add_co_u32_e32 v2, vcc, s0, v2
	v_permlane32_swap_b32_e32 v6, v8
	v_permlane32_swap_b32_e32 v7, v9
	v_addc_co_u32_e32 v3, vcc, 0, v3, vcc
	global_store_dwordx4 v[2:3], v[6:9], off offset:1536
	s_waitcnt vmcnt(3)
	v_mov_b32_e32 v10, v66
	s_nop 1
	v_mov_b32_e32 v6, v64
	s_nop 1
	v_permlane32_swap_b32_e32 v6, v10
	v_lshlrev_b32_e32 v8, 16, v6
	v_and_b32_e32 v6, 0xffff0000, v6
	v_mul_f32_e32 v2, 0xbfb8aa3b, v8
	v_mul_f32_e32 v3, 0xbfb8aa3b, v6
	v_exp_f32_e32 v2, v2
	v_exp_f32_e32 v3, v3
	v_mov_b32_e32 v12, v67
	s_nop 1
	v_mov_b32_e32 v7, v65
	s_nop 1
	v_permlane32_swap_b32_e32 v7, v12
	v_pk_add_f32 v[2:3], v[2:3], 1.0 op_sel_hi:[1,0]
	s_nop 0
	v_div_scale_f32 v9, s[0:1], v3, v3, v6
	v_rcp_f32_e32 v11, v9
	s_nop 0
	v_fma_f32 v13, -v9, v11, 1.0
	v_fmac_f32_e32 v11, v13, v11
	v_div_scale_f32 v13, vcc, v6, v3, v6
	v_mul_f32_e32 v14, v13, v11
	v_fma_f32 v15, -v9, v14, v13
	v_fmac_f32_e32 v14, v15, v11
	v_fma_f32 v9, -v9, v14, v13
	v_div_fmas_f32 v9, v9, v11, v14
	v_div_fixup_f32 v3, v9, v3, v6
	v_div_scale_f32 v6, s[0:1], v2, v2, v8
	v_rcp_f32_e32 v9, v6
	s_nop 0
	v_fma_f32 v11, -v6, v9, 1.0
	v_fmac_f32_e32 v9, v11, v9
	v_div_scale_f32 v11, vcc, v8, v2, v8
	v_mul_f32_e32 v13, v11, v9
	v_fma_f32 v14, -v6, v13, v11
	v_fmac_f32_e32 v13, v14, v9
	v_fma_f32 v6, -v6, v13, v11
	v_div_fmas_f32 v6, v6, v9, v13
	v_div_fixup_f32 v2, v6, v2, v8
	v_lshlrev_b32_e32 v8, 16, v7
	v_and_b32_e32 v9, 0xffff0000, v7
	v_mul_f32_e32 v6, 0xbfb8aa3b, v8
	v_mul_f32_e32 v7, 0xbfb8aa3b, v9
	v_exp_f32_e32 v6, v6
	v_exp_f32_e32 v7, v7
	v_pk_mul_f32 v[2:3], v[56:57], v[2:3]
	v_pk_add_f32 v[6:7], v[6:7], 1.0 op_sel_hi:[1,0]
	s_nop 0
	v_div_scale_f32 v11, s[0:1], v7, v7, v9
	v_rcp_f32_e32 v13, v11
	s_nop 0
	v_fma_f32 v14, -v11, v13, 1.0
	v_fmac_f32_e32 v13, v14, v13
	v_div_scale_f32 v14, vcc, v9, v7, v9
	v_mul_f32_e32 v15, v14, v13
	v_fma_f32 v16, -v11, v15, v14
	v_fmac_f32_e32 v15, v16, v13
	v_fma_f32 v11, -v11, v15, v14
	v_div_fmas_f32 v11, v11, v13, v15
	v_div_fixup_f32 v7, v11, v7, v9
	v_div_scale_f32 v9, s[0:1], v6, v6, v8
	v_rcp_f32_e32 v11, v9
	s_nop 0
	v_fma_f32 v13, -v9, v11, 1.0
	v_fmac_f32_e32 v11, v13, v11
	v_div_scale_f32 v13, vcc, v8, v6, v8
	v_mul_f32_e32 v14, v13, v11
	v_fma_f32 v15, -v9, v14, v13
	v_fmac_f32_e32 v14, v15, v11
	v_fma_f32 v9, -v9, v14, v13
	v_div_fmas_f32 v9, v9, v11, v14
	v_div_fixup_f32 v6, v9, v6, v8
	v_lshlrev_b32_e32 v11, 16, v10
	v_and_b32_e32 v10, 0xffff0000, v10
	v_pk_mul_f32 v[8:9], v[58:59], v[6:7]
	v_mul_f32_e32 v6, 0xbfb8aa3b, v11
	v_mul_f32_e32 v7, 0xbfb8aa3b, v10
	v_exp_f32_e32 v6, v6
	v_exp_f32_e32 v7, v7
	s_nop 0
	v_pk_add_f32 v[6:7], v[6:7], 1.0 op_sel_hi:[1,0]
	s_nop 0
	v_div_scale_f32 v13, s[0:1], v7, v7, v10
	v_rcp_f32_e32 v14, v13
	s_nop 0
	v_fma_f32 v15, -v13, v14, 1.0
	v_fmac_f32_e32 v14, v15, v14
	v_div_scale_f32 v15, vcc, v10, v7, v10
	v_mul_f32_e32 v16, v15, v14
	v_fma_f32 v17, -v13, v16, v15
	v_fmac_f32_e32 v16, v17, v14
	v_fma_f32 v13, -v13, v16, v15
	v_div_fmas_f32 v13, v13, v14, v16
	v_div_fixup_f32 v7, v13, v7, v10
	v_div_scale_f32 v10, s[0:1], v6, v6, v11
	v_rcp_f32_e32 v13, v10
	s_nop 0
	v_fma_f32 v14, -v10, v13, 1.0
	v_fmac_f32_e32 v13, v14, v13
	v_div_scale_f32 v14, vcc, v11, v6, v11
	v_mul_f32_e32 v15, v14, v13
	v_fma_f32 v16, -v10, v15, v14
	v_fmac_f32_e32 v15, v16, v13
	v_fma_f32 v10, -v10, v15, v14
	v_div_fmas_f32 v10, v10, v13, v15
	v_div_fixup_f32 v6, v10, v6, v11
	v_lshlrev_b32_e32 v13, 16, v12
	v_and_b32_e32 v12, 0xffff0000, v12
	v_pk_mul_f32 v[10:11], v[60:61], v[6:7]
	v_mul_f32_e32 v6, 0xbfb8aa3b, v13
	v_mul_f32_e32 v7, 0xbfb8aa3b, v12
	v_exp_f32_e32 v6, v6
	v_exp_f32_e32 v7, v7
	s_nop 0
	v_pk_add_f32 v[6:7], v[6:7], 1.0 op_sel_hi:[1,0]
	s_nop 0
	v_div_scale_f32 v14, s[0:1], v7, v7, v12
	v_rcp_f32_e32 v15, v14
	s_nop 0
	v_fma_f32 v16, -v14, v15, 1.0
	v_fmac_f32_e32 v15, v16, v15
	v_div_scale_f32 v16, vcc, v12, v7, v12
	v_mul_f32_e32 v17, v16, v15
	v_fma_f32 v18, -v14, v17, v16
	v_fmac_f32_e32 v17, v18, v15
	v_fma_f32 v14, -v14, v17, v16
	v_div_fmas_f32 v14, v14, v15, v17
	v_div_fixup_f32 v7, v14, v7, v12
	v_div_scale_f32 v12, s[0:1], v6, v6, v13
	v_rcp_f32_e32 v14, v12
	s_nop 0
	v_fma_f32 v15, -v12, v14, 1.0
	v_fmac_f32_e32 v14, v15, v14
	v_div_scale_f32 v15, vcc, v13, v6, v13
	v_mul_f32_e32 v16, v15, v14
	v_fma_f32 v17, -v12, v16, v15
	v_fmac_f32_e32 v16, v17, v14
	v_fma_f32 v12, -v12, v16, v15
	v_div_fmas_f32 v12, v12, v14, v16
	v_div_fixup_f32 v6, v12, v6, v13
	v_pk_mul_f32 v[12:13], v[62:63], v[6:7]
	v_cvt_pk_bf16_f32 v6, v2, v3
	v_cvt_pk_bf16_f32 v7, v8, v9
	v_cvt_pk_bf16_f32 v8, v10, v11
	v_cvt_pk_bf16_f32 v9, v12, v13
	s_nop 0
	v_permlane32_swap_b32_e32 v6, v8
	v_permlane32_swap_b32_e32 v7, v9
	global_store_dwordx4 v[4:5], v[6:9], off offset:32
	s_waitcnt vmcnt(3)
	v_mov_b32_e32 v10, v70
	s_nop 1
	v_mov_b32_e32 v6, v68
	s_nop 1
	v_permlane32_swap_b32_e32 v6, v10
	v_lshlrev_b32_e32 v8, 16, v6
	v_and_b32_e32 v6, 0xffff0000, v6
	v_mul_f32_e32 v2, 0xbfb8aa3b, v8
	v_mul_f32_e32 v3, 0xbfb8aa3b, v6
	v_exp_f32_e32 v2, v2
	v_exp_f32_e32 v3, v3
	v_mov_b32_e32 v12, v71
	s_nop 1
	v_mov_b32_e32 v7, v69
	s_nop 1
	v_permlane32_swap_b32_e32 v7, v12
	v_pk_add_f32 v[2:3], v[2:3], 1.0 op_sel_hi:[1,0]
	s_nop 0
	v_div_scale_f32 v9, s[0:1], v3, v3, v6
	v_rcp_f32_e32 v11, v9
	s_nop 0
	v_fma_f32 v13, -v9, v11, 1.0
	v_fmac_f32_e32 v11, v13, v11
	v_div_scale_f32 v13, vcc, v6, v3, v6
	v_mul_f32_e32 v14, v13, v11
	v_fma_f32 v15, -v9, v14, v13
	v_fmac_f32_e32 v14, v15, v11
	v_fma_f32 v9, -v9, v14, v13
	v_div_fmas_f32 v9, v9, v11, v14
	v_div_fixup_f32 v3, v9, v3, v6
	v_div_scale_f32 v6, s[0:1], v2, v2, v8
	v_rcp_f32_e32 v9, v6
	s_nop 0
	v_fma_f32 v11, -v6, v9, 1.0
	v_fmac_f32_e32 v9, v11, v9
	v_div_scale_f32 v11, vcc, v8, v2, v8
	v_mul_f32_e32 v13, v11, v9
	v_fma_f32 v14, -v6, v13, v11
	v_fmac_f32_e32 v13, v14, v9
	v_fma_f32 v6, -v6, v13, v11
	v_div_fmas_f32 v6, v6, v9, v13
	v_div_fixup_f32 v2, v6, v2, v8
	v_lshlrev_b32_e32 v8, 16, v7
	v_and_b32_e32 v9, 0xffff0000, v7
	v_mul_f32_e32 v6, 0xbfb8aa3b, v8
	v_mul_f32_e32 v7, 0xbfb8aa3b, v9
	v_exp_f32_e32 v6, v6
	v_exp_f32_e32 v7, v7
	v_pk_mul_f32 v[2:3], v[32:33], v[2:3]
	v_pk_add_f32 v[6:7], v[6:7], 1.0 op_sel_hi:[1,0]
	s_nop 0
	v_div_scale_f32 v11, s[0:1], v7, v7, v9
	v_rcp_f32_e32 v13, v11
	s_nop 0
	v_fma_f32 v14, -v11, v13, 1.0
	v_fmac_f32_e32 v13, v14, v13
	v_div_scale_f32 v14, vcc, v9, v7, v9
	v_mul_f32_e32 v15, v14, v13
	v_fma_f32 v16, -v11, v15, v14
	v_fmac_f32_e32 v15, v16, v13
	v_fma_f32 v11, -v11, v15, v14
	v_div_fmas_f32 v11, v11, v13, v15
	v_div_fixup_f32 v7, v11, v7, v9
	v_div_scale_f32 v9, s[0:1], v6, v6, v8
	v_rcp_f32_e32 v11, v9
	s_nop 0
	v_fma_f32 v13, -v9, v11, 1.0
	v_fmac_f32_e32 v11, v13, v11
	v_div_scale_f32 v13, vcc, v8, v6, v8
	v_mul_f32_e32 v14, v13, v11
	v_fma_f32 v15, -v9, v14, v13
	v_fmac_f32_e32 v14, v15, v11
	v_fma_f32 v9, -v9, v14, v13
	v_div_fmas_f32 v9, v9, v11, v14
	v_div_fixup_f32 v6, v9, v6, v8
	v_lshlrev_b32_e32 v11, 16, v10
	v_and_b32_e32 v10, 0xffff0000, v10
	v_pk_mul_f32 v[8:9], v[34:35], v[6:7]
	v_mul_f32_e32 v6, 0xbfb8aa3b, v11
	v_mul_f32_e32 v7, 0xbfb8aa3b, v10
	v_exp_f32_e32 v6, v6
	v_exp_f32_e32 v7, v7
	s_nop 0
	v_pk_add_f32 v[6:7], v[6:7], 1.0 op_sel_hi:[1,0]
	s_nop 0
	v_div_scale_f32 v13, s[0:1], v7, v7, v10
	v_rcp_f32_e32 v14, v13
	s_nop 0
	v_fma_f32 v15, -v13, v14, 1.0
	v_fmac_f32_e32 v14, v15, v14
	v_div_scale_f32 v15, vcc, v10, v7, v10
	v_mul_f32_e32 v16, v15, v14
	v_fma_f32 v17, -v13, v16, v15
	v_fmac_f32_e32 v16, v17, v14
	v_fma_f32 v13, -v13, v16, v15
	v_div_fmas_f32 v13, v13, v14, v16
	v_div_fixup_f32 v7, v13, v7, v10
	v_div_scale_f32 v10, s[0:1], v6, v6, v11
	v_rcp_f32_e32 v13, v10
	s_nop 0
	v_fma_f32 v14, -v10, v13, 1.0
	v_fmac_f32_e32 v13, v14, v13
	v_div_scale_f32 v14, vcc, v11, v6, v11
	v_mul_f32_e32 v15, v14, v13
	v_fma_f32 v16, -v10, v15, v14
	v_fmac_f32_e32 v15, v16, v13
	v_fma_f32 v10, -v10, v15, v14
	v_div_fmas_f32 v10, v10, v13, v15
	v_div_fixup_f32 v6, v10, v6, v11
	v_lshlrev_b32_e32 v13, 16, v12
	v_and_b32_e32 v12, 0xffff0000, v12
	v_pk_mul_f32 v[10:11], v[36:37], v[6:7]
	v_mul_f32_e32 v6, 0xbfb8aa3b, v13
	v_mul_f32_e32 v7, 0xbfb8aa3b, v12
	v_exp_f32_e32 v6, v6
	v_exp_f32_e32 v7, v7
	s_nop 0
	v_pk_add_f32 v[6:7], v[6:7], 1.0 op_sel_hi:[1,0]
	s_nop 0
	v_div_scale_f32 v14, s[0:1], v7, v7, v12
	v_rcp_f32_e32 v15, v14
	s_nop 0
	v_fma_f32 v16, -v14, v15, 1.0
	v_fmac_f32_e32 v15, v16, v15
	v_div_scale_f32 v16, vcc, v12, v7, v12
	v_mul_f32_e32 v17, v16, v15
	v_fma_f32 v18, -v14, v17, v16
	v_fmac_f32_e32 v17, v18, v15
	v_fma_f32 v14, -v14, v17, v16
	v_div_fmas_f32 v14, v14, v15, v17
	v_div_fixup_f32 v7, v14, v7, v12
	v_div_scale_f32 v12, s[0:1], v6, v6, v13
	v_rcp_f32_e32 v14, v12
	s_nop 0
	v_fma_f32 v15, -v12, v14, 1.0
	v_fmac_f32_e32 v14, v15, v14
	v_div_scale_f32 v15, vcc, v13, v6, v13
	v_mul_f32_e32 v16, v15, v14
	v_fma_f32 v17, -v12, v16, v15
	v_fmac_f32_e32 v16, v17, v14
	v_fma_f32 v12, -v12, v16, v15
	v_div_fmas_f32 v12, v12, v14, v16
	v_div_fixup_f32 v6, v12, v6, v13
	v_pk_mul_f32 v[12:13], v[38:39], v[6:7]
	v_cvt_pk_bf16_f32 v6, v2, v3
	v_cvt_pk_bf16_f32 v7, v8, v9
	v_cvt_pk_bf16_f32 v8, v10, v11
	v_cvt_pk_bf16_f32 v9, v12, v13
	s_nop 0
	v_permlane32_swap_b32_e32 v6, v8
	v_permlane32_swap_b32_e32 v7, v9
	global_store_dwordx4 v[4:5], v[6:9], off offset:64
	s_waitcnt vmcnt(3)
	v_mov_b32_e32 v10, v75
	v_mov_b32_e32 v8, v74
	s_nop 1
	v_mov_b32_e32 v0, v72
	s_nop 1
	v_permlane32_swap_b32_e32 v0, v8
	v_lshlrev_b32_e32 v6, 16, v0
	v_and_b32_e32 v0, 0xffff0000, v0
	v_mul_f32_e32 v2, 0xbfb8aa3b, v6
	v_mul_f32_e32 v3, 0xbfb8aa3b, v0
	v_exp_f32_e32 v2, v2
	v_exp_f32_e32 v3, v3
	v_mov_b32_e32 v1, v73
	s_nop 1
	v_permlane32_swap_b32_e32 v1, v10
	v_pk_add_f32 v[2:3], v[2:3], 1.0 op_sel_hi:[1,0]
	s_nop 0
	v_div_scale_f32 v7, s[0:1], v3, v3, v0
	v_rcp_f32_e32 v9, v7
	s_nop 0
	v_fma_f32 v11, -v7, v9, 1.0
	v_fmac_f32_e32 v9, v11, v9
	v_div_scale_f32 v11, vcc, v0, v3, v0
	v_mul_f32_e32 v12, v11, v9
	v_fma_f32 v13, -v7, v12, v11
	v_fmac_f32_e32 v12, v13, v9
	v_fma_f32 v7, -v7, v12, v11
	v_div_fmas_f32 v7, v7, v9, v12
	v_div_fixup_f32 v3, v7, v3, v0
	v_div_scale_f32 v0, s[0:1], v2, v2, v6
	v_rcp_f32_e32 v7, v0
	s_nop 0
	v_fma_f32 v9, -v0, v7, 1.0
	v_fmac_f32_e32 v7, v9, v7
	v_div_scale_f32 v9, vcc, v6, v2, v6
	v_mul_f32_e32 v11, v9, v7
	v_fma_f32 v12, -v0, v11, v9
	v_fmac_f32_e32 v11, v12, v7
	v_fma_f32 v0, -v0, v11, v9
	v_div_fmas_f32 v0, v0, v7, v11
	v_div_fixup_f32 v2, v0, v2, v6
	v_lshlrev_b32_e32 v6, 16, v1
	v_and_b32_e32 v7, 0xffff0000, v1
	v_mul_f32_e32 v0, 0xbfb8aa3b, v6
	v_mul_f32_e32 v1, 0xbfb8aa3b, v7
	v_exp_f32_e32 v0, v0
	v_exp_f32_e32 v1, v1
	v_pk_mul_f32 v[2:3], v[40:41], v[2:3]
	v_pk_add_f32 v[0:1], v[0:1], 1.0 op_sel_hi:[1,0]
	s_nop 0
	v_div_scale_f32 v9, s[0:1], v1, v1, v7
	v_rcp_f32_e32 v11, v9
	s_nop 0
	v_fma_f32 v12, -v9, v11, 1.0
	v_fmac_f32_e32 v11, v12, v11
	v_div_scale_f32 v12, vcc, v7, v1, v7
	v_mul_f32_e32 v13, v12, v11
	v_fma_f32 v14, -v9, v13, v12
	v_fmac_f32_e32 v13, v14, v11
	v_fma_f32 v9, -v9, v13, v12
	v_div_fmas_f32 v9, v9, v11, v13
	v_div_fixup_f32 v1, v9, v1, v7
	v_div_scale_f32 v7, s[0:1], v0, v0, v6
	v_rcp_f32_e32 v9, v7
	s_nop 0
	v_fma_f32 v11, -v7, v9, 1.0
	v_fmac_f32_e32 v9, v11, v9
	v_div_scale_f32 v11, vcc, v6, v0, v6
	v_mul_f32_e32 v12, v11, v9
	v_fma_f32 v13, -v7, v12, v11
	v_fmac_f32_e32 v12, v13, v9
	v_fma_f32 v7, -v7, v12, v11
	v_div_fmas_f32 v7, v7, v9, v12
	v_div_fixup_f32 v0, v7, v0, v6
	v_lshlrev_b32_e32 v9, 16, v8
	v_and_b32_e32 v8, 0xffff0000, v8
	v_pk_mul_f32 v[6:7], v[42:43], v[0:1]
	v_mul_f32_e32 v0, 0xbfb8aa3b, v9
	v_mul_f32_e32 v1, 0xbfb8aa3b, v8
	v_exp_f32_e32 v0, v0
	v_exp_f32_e32 v1, v1
	s_nop 0
	v_pk_add_f32 v[0:1], v[0:1], 1.0 op_sel_hi:[1,0]
	s_nop 0
	v_div_scale_f32 v11, s[0:1], v1, v1, v8
	v_rcp_f32_e32 v12, v11
	s_nop 0
	v_fma_f32 v13, -v11, v12, 1.0
	v_fmac_f32_e32 v12, v13, v12
	v_div_scale_f32 v13, vcc, v8, v1, v8
	v_mul_f32_e32 v14, v13, v12
	v_fma_f32 v15, -v11, v14, v13
	v_fmac_f32_e32 v14, v15, v12
	v_fma_f32 v11, -v11, v14, v13
	v_div_fmas_f32 v11, v11, v12, v14
	v_div_fixup_f32 v1, v11, v1, v8
	v_div_scale_f32 v8, s[0:1], v0, v0, v9
	v_rcp_f32_e32 v11, v8
	s_nop 0
	v_fma_f32 v12, -v8, v11, 1.0
	v_fmac_f32_e32 v11, v12, v11
	v_div_scale_f32 v12, vcc, v9, v0, v9
	v_mul_f32_e32 v13, v12, v11
	v_fma_f32 v14, -v8, v13, v12
	v_fmac_f32_e32 v13, v14, v11
	v_fma_f32 v8, -v8, v13, v12
	v_div_fmas_f32 v8, v8, v11, v13
	v_div_fixup_f32 v0, v8, v0, v9
	v_lshlrev_b32_e32 v11, 16, v10
	v_and_b32_e32 v10, 0xffff0000, v10
	v_pk_mul_f32 v[8:9], v[44:45], v[0:1]
	v_mul_f32_e32 v0, 0xbfb8aa3b, v11
	v_mul_f32_e32 v1, 0xbfb8aa3b, v10
	v_exp_f32_e32 v0, v0
	v_exp_f32_e32 v1, v1
	s_nop 0
	v_pk_add_f32 v[0:1], v[0:1], 1.0 op_sel_hi:[1,0]
	s_nop 0
	v_div_scale_f32 v12, s[0:1], v1, v1, v10
	v_rcp_f32_e32 v13, v12
	s_nop 0
	v_fma_f32 v14, -v12, v13, 1.0
	v_fmac_f32_e32 v13, v14, v13
	v_div_scale_f32 v14, vcc, v10, v1, v10
	v_mul_f32_e32 v15, v14, v13
	v_fma_f32 v16, -v12, v15, v14
	v_fmac_f32_e32 v15, v16, v13
	v_fma_f32 v12, -v12, v15, v14
	v_div_fmas_f32 v12, v12, v13, v15
	v_div_fixup_f32 v1, v12, v1, v10
	v_div_scale_f32 v10, s[0:1], v0, v0, v11
	v_rcp_f32_e32 v12, v10
	s_nop 0
	v_fma_f32 v13, -v10, v12, 1.0
	v_fmac_f32_e32 v12, v13, v12
	v_div_scale_f32 v13, vcc, v11, v0, v11
	v_mul_f32_e32 v14, v13, v12
	v_fma_f32 v15, -v10, v14, v13
	v_fmac_f32_e32 v14, v15, v12
	v_fma_f32 v10, -v10, v14, v13
	v_div_fmas_f32 v10, v10, v12, v14
	v_div_fixup_f32 v0, v10, v0, v11
	v_pk_mul_f32 v[10:11], v[46:47], v[0:1]
	v_cvt_pk_bf16_f32 v0, v2, v3
	v_cvt_pk_bf16_f32 v1, v6, v7
	v_cvt_pk_bf16_f32 v2, v8, v9
	v_cvt_pk_bf16_f32 v3, v10, v11
	s_nop 0
	v_permlane32_swap_b32_e32 v0, v2
	v_permlane32_swap_b32_e32 v1, v3
	global_store_dwordx4 v[4:5], v[0:3], off offset:96

.LBB0_714:
	v_cmp_lt_i32_e32 vcc, v109, v111
	v_lshlrev_b32_e32 v192, 1, v108
	v_readlane_b32 s76, v254, 37
	v_cndmask_b32_e32 v32, v110, v109, vcc
	v_lshlrev_b32_e32 v32, 2, v32
	ds_bpermute_b32 v32, v32, v34
	v_readlane_b32 s77, v254, 38
	s_waitcnt lgkmcnt(0)
	v_add_f32_e32 v32, v34, v32
	v_div_scale_f32 v33, s[0:1], v32, v32, 1.0
	v_rcp_f32_e32 v34, v33
	v_readlane_b32 s0, v254, 9
	v_readlane_b32 s1, v254, 10
	v_fma_f32 v35, -v33, v34, 1.0
	v_fmac_f32_e32 v34, v35, v34
	v_div_scale_f32 v35, vcc, 1.0, v32, 1.0
	v_mul_f32_e32 v36, v35, v34
	v_fma_f32 v37, -v33, v36, v35
	v_fmac_f32_e32 v36, v37, v34
	v_fma_f32 v33, -v33, v36, v35
	v_div_fmas_f32 v33, v33, v34, v36
	global_load_dwordx4 v[36:39], v[96:97], off offset:1536
	global_load_dwordx4 v[64:67], v[96:97], off offset:1568
	global_load_dwordx4 v[68:71], v[96:97], off offset:1600
	global_load_dwordx4 v[72:75], v[96:97], off offset:1632
	v_readlane_b32 s98, v253, 59
	v_readlane_b32 s99, v253, 60
	s_nop 1
	v_writelane_b32 v76, s98, 40
	v_writelane_b32 v77, s99, 40
	s_mov_b64 s[98:99], exec
	v_cmpx_eq_u32_e64 exec, 40, v234
	s_nop 3
	v_writelane_b32 v255, exec_hi, 41
	global_atomic_add v255, v[76:77], v251, off sc0
	s_mov_b64 exec, s[98:99]
	v_div_fixup_f32 v34, v33, v32, 1.0
	v_lshlrev_b64 v[32:33], 11, v[98:99]
	v_lshl_add_u64 v[32:33], s[0:1], 0, v[32:33]
	s_mov_b64 s[0:1], 0x3e38aa3b
	s_mov_b32 s15, s1
	v_lshl_add_u64 v[32:33], v[32:33], 0, s[14:15]
	v_lshl_add_u64 v[32:33], v[32:33], 0, v[192:193]
	s_waitcnt vmcnt(3)
	v_mov_b32_e32 v35, v38
	s_nop 1
	v_permlane32_swap_b32_e32 v36, v35
	v_lshlrev_b32_e32 v41, 16, v36
	v_and_b32_e32 v36, 0xffff0000, v36
	v_mov_b32_e32 v40, v39
	v_mul_f32_e32 v38, 0xbfb8aa3b, v41
	v_mul_f32_e32 v39, 0xbfb8aa3b, v36
	v_exp_f32_e32 v38, v38
	v_exp_f32_e32 v39, v39
	v_permlane32_swap_b32_e32 v37, v40
	v_pk_mul_f32 v[16:17], v[16:17], v[34:35] op_sel_hi:[1,0]
	v_pk_add_f32 v[38:39], v[38:39], 1.0 op_sel_hi:[1,0]
	v_pk_mul_f32 v[18:19], v[18:19], v[34:35] op_sel_hi:[1,0]
	v_div_scale_f32 v42, s[0:1], v39, v39, v36
	v_rcp_f32_e32 v43, v42
	s_nop 0
	v_fma_f32 v44, -v42, v43, 1.0
	v_fmac_f32_e32 v43, v44, v43
	v_div_scale_f32 v44, vcc, v36, v39, v36
	v_mul_f32_e32 v45, v44, v43
	v_fma_f32 v46, -v42, v45, v44
	v_fmac_f32_e32 v45, v46, v43
	v_fma_f32 v42, -v42, v45, v44
	v_div_fmas_f32 v42, v42, v43, v45
	v_div_fixup_f32 v39, v42, v39, v36
	v_div_scale_f32 v36, s[0:1], v38, v38, v41
	v_rcp_f32_e32 v42, v36
	s_nop 0
	v_fma_f32 v43, -v36, v42, 1.0
	v_fmac_f32_e32 v42, v43, v42
	v_div_scale_f32 v43, vcc, v41, v38, v41
	v_mul_f32_e32 v44, v43, v42
	v_fma_f32 v45, -v36, v44, v43
	v_fmac_f32_e32 v44, v45, v42
	v_fma_f32 v36, -v36, v44, v43
	v_div_fmas_f32 v36, v36, v42, v44
	v_div_fixup_f32 v38, v36, v38, v41
	v_pk_mul_f32 v[16:17], v[16:17], v[38:39]
	v_lshlrev_b32_e32 v38, 16, v37
	v_and_b32_e32 v39, 0xffff0000, v37
	v_mul_f32_e32 v36, 0xbfb8aa3b, v38
	v_mul_f32_e32 v37, 0xbfb8aa3b, v39
	v_exp_f32_e32 v36, v36
	v_exp_f32_e32 v37, v37
	v_cvt_pk_bf16_f32 v16, v16, v17
	v_pk_add_f32 v[36:37], v[36:37], 1.0 op_sel_hi:[1,0]
	s_nop 0
	v_div_scale_f32 v41, s[0:1], v37, v37, v39
	v_rcp_f32_e32 v42, v41
	s_nop 0
	v_fma_f32 v43, -v41, v42, 1.0
	v_fmac_f32_e32 v42, v43, v42
	v_div_scale_f32 v43, vcc, v39, v37, v39
	v_mul_f32_e32 v44, v43, v42
	v_fma_f32 v45, -v41, v44, v43
	v_fmac_f32_e32 v44, v45, v42
	v_fma_f32 v41, -v41, v44, v43
	v_div_fmas_f32 v41, v41, v42, v44
	v_div_fixup_f32 v37, v41, v37, v39
	v_div_scale_f32 v39, s[0:1], v36, v36, v38
	v_rcp_f32_e32 v41, v39
	s_nop 0
	v_fma_f32 v42, -v39, v41, 1.0
	v_fmac_f32_e32 v41, v42, v41
	v_div_scale_f32 v42, vcc, v38, v36, v38
	v_mul_f32_e32 v43, v42, v41
	v_fma_f32 v44, -v39, v43, v42
	v_fmac_f32_e32 v43, v44, v41
	v_fma_f32 v39, -v39, v43, v42
	v_div_fmas_f32 v39, v39, v41, v43
	v_div_fixup_f32 v36, v39, v36, v38
	v_lshlrev_b32_e32 v38, 16, v35
	v_and_b32_e32 v35, 0xffff0000, v35
	v_pk_mul_f32 v[18:19], v[18:19], v[36:37]
	v_mul_f32_e32 v36, 0xbfb8aa3b, v38
	v_mul_f32_e32 v37, 0xbfb8aa3b, v35
	v_exp_f32_e32 v36, v36
	v_exp_f32_e32 v37, v37
	v_pk_mul_f32 v[20:21], v[20:21], v[34:35] op_sel_hi:[1,0]
	v_cvt_pk_bf16_f32 v17, v18, v19
	v_pk_add_f32 v[36:37], v[36:37], 1.0 op_sel_hi:[1,0]
	s_nop 0
	v_div_scale_f32 v39, s[0:1], v37, v37, v35
	v_rcp_f32_e32 v41, v39
	s_nop 0
	v_fma_f32 v42, -v39, v41, 1.0
	v_fmac_f32_e32 v41, v42, v41
	v_div_scale_f32 v42, vcc, v35, v37, v35
	v_mul_f32_e32 v43, v42, v41
	v_fma_f32 v44, -v39, v43, v42
	v_fmac_f32_e32 v43, v44, v41
	v_fma_f32 v39, -v39, v43, v42
	v_div_fmas_f32 v39, v39, v41, v43
	v_div_fixup_f32 v37, v39, v37, v35
	v_div_scale_f32 v35, s[0:1], v36, v36, v38
	v_rcp_f32_e32 v39, v35
	s_nop 0
	v_fma_f32 v41, -v35, v39, 1.0
	v_fmac_f32_e32 v39, v41, v39
	v_div_scale_f32 v41, vcc, v38, v36, v38
	v_mul_f32_e32 v42, v41, v39
	v_fma_f32 v43, -v35, v42, v41
	v_fmac_f32_e32 v42, v43, v39
	v_fma_f32 v35, -v35, v42, v41
	v_div_fmas_f32 v35, v35, v39, v42
	v_div_fixup_f32 v36, v35, v36, v38
	v_lshlrev_b32_e32 v35, 16, v40
	v_and_b32_e32 v38, 0xffff0000, v40
	v_pk_mul_f32 v[20:21], v[20:21], v[36:37]
	v_mul_f32_e32 v36, 0xbfb8aa3b, v35
	v_mul_f32_e32 v37, 0xbfb8aa3b, v38
	v_exp_f32_e32 v36, v36
	v_exp_f32_e32 v37, v37
	v_pk_mul_f32 v[22:23], v[22:23], v[34:35] op_sel_hi:[1,0]
	v_cvt_pk_bf16_f32 v18, v20, v21
	s_nop 1
	v_permlane32_swap_b32_e32 v16, v18
	v_pk_add_f32 v[36:37], v[36:37], 1.0 op_sel_hi:[1,0]
	s_nop 0
	v_div_scale_f32 v39, s[0:1], v37, v37, v38
	v_rcp_f32_e32 v40, v39
	s_nop 0
	v_fma_f32 v41, -v39, v40, 1.0
	v_fmac_f32_e32 v40, v41, v40
	v_div_scale_f32 v41, vcc, v38, v37, v38
	v_mul_f32_e32 v42, v41, v40
	v_fma_f32 v43, -v39, v42, v41
	v_fmac_f32_e32 v42, v43, v40
	v_fma_f32 v39, -v39, v42, v41
	v_div_fmas_f32 v39, v39, v40, v42
	v_div_fixup_f32 v37, v39, v37, v38
	v_div_scale_f32 v38, s[0:1], v36, v36, v35
	v_rcp_f32_e32 v39, v38
	s_nop 0
	v_fma_f32 v40, -v38, v39, 1.0
	v_fmac_f32_e32 v39, v40, v39
	v_div_scale_f32 v40, vcc, v35, v36, v35
	v_mul_f32_e32 v41, v40, v39
	v_fma_f32 v42, -v38, v41, v40
	v_fmac_f32_e32 v41, v42, v39
	v_fma_f32 v38, -v38, v41, v40
	v_div_fmas_f32 v38, v38, v39, v41
	v_div_fixup_f32 v36, v38, v36, v35
	v_pk_mul_f32 v[22:23], v[22:23], v[36:37]
	s_nop 0
	v_cvt_pk_bf16_f32 v19, v22, v23
	s_nop 1
	v_permlane32_swap_b32_e32 v17, v19
	global_store_dwordx4 v[32:33], v[16:19], off
	s_waitcnt vmcnt(3)
	v_mov_b32_e32 v22, v66
	s_nop 1
	v_mov_b32_e32 v16, v64
	s_nop 1
	v_permlane32_swap_b32_e32 v16, v22
	v_lshlrev_b32_e32 v23, 16, v16
	v_and_b32_e32 v16, 0xffff0000, v16
	v_mul_f32_e32 v20, 0xbfb8aa3b, v23
	v_mul_f32_e32 v21, 0xbfb8aa3b, v16
	v_exp_f32_e32 v20, v20
	v_exp_f32_e32 v21, v21
	v_mov_b32_e32 v35, v67
	s_nop 1
	v_mov_b32_e32 v17, v65
	s_nop 1
	v_permlane32_swap_b32_e32 v17, v35
	v_pk_add_f32 v[20:21], v[20:21], 1.0 op_sel_hi:[1,0]
	v_pk_mul_f32 v[18:19], v[24:25], v[34:35] op_sel_hi:[1,0]
	v_div_scale_f32 v24, s[0:1], v21, v21, v16
	v_rcp_f32_e32 v25, v24
	s_nop 0
	v_fma_f32 v36, -v24, v25, 1.0
	v_fmac_f32_e32 v25, v36, v25
	v_div_scale_f32 v36, vcc, v16, v21, v16
	v_mul_f32_e32 v37, v36, v25
	v_fma_f32 v38, -v24, v37, v36
	v_fmac_f32_e32 v37, v38, v25
	v_fma_f32 v24, -v24, v37, v36
	v_div_fmas_f32 v24, v24, v25, v37
	v_div_fixup_f32 v21, v24, v21, v16
	v_div_scale_f32 v16, s[0:1], v20, v20, v23
	v_rcp_f32_e32 v24, v16
	s_nop 0
	v_fma_f32 v25, -v16, v24, 1.0
	v_fmac_f32_e32 v24, v25, v24
	v_div_scale_f32 v25, vcc, v23, v20, v23
	v_mul_f32_e32 v36, v25, v24
	v_fma_f32 v37, -v16, v36, v25
	v_fmac_f32_e32 v36, v37, v24
	v_fma_f32 v16, -v16, v36, v25
	v_div_fmas_f32 v16, v16, v24, v36
	v_div_fixup_f32 v20, v16, v20, v23
	v_lshlrev_b32_e32 v23, 16, v17
	v_and_b32_e32 v24, 0xffff0000, v17
	v_pk_mul_f32 v[18:19], v[18:19], v[20:21]
	v_mul_f32_e32 v20, 0xbfb8aa3b, v23
	v_mul_f32_e32 v21, 0xbfb8aa3b, v24
	v_exp_f32_e32 v20, v20
	v_exp_f32_e32 v21, v21
	v_pk_mul_f32 v[16:17], v[26:27], v[34:35] op_sel_hi:[1,0]
	v_pk_add_f32 v[20:21], v[20:21], 1.0 op_sel_hi:[1,0]
	s_nop 0
	v_div_scale_f32 v25, s[0:1], v21, v21, v24
	v_rcp_f32_e32 v26, v25
	s_nop 0
	v_fma_f32 v27, -v25, v26, 1.0
	v_fmac_f32_e32 v26, v27, v26
	v_div_scale_f32 v27, vcc, v24, v21, v24
	v_mul_f32_e32 v36, v27, v26
	v_fma_f32 v37, -v25, v36, v27
	v_fmac_f32_e32 v36, v37, v26
	v_fma_f32 v25, -v25, v36, v27
	v_div_fmas_f32 v25, v25, v26, v36
	v_div_fixup_f32 v21, v25, v21, v24
	v_div_scale_f32 v24, s[0:1], v20, v20, v23
	v_rcp_f32_e32 v25, v24
	s_nop 0
	v_fma_f32 v26, -v24, v25, 1.0
	v_fmac_f32_e32 v25, v26, v25
	v_div_scale_f32 v26, vcc, v23, v20, v23
	v_mul_f32_e32 v27, v26, v25
	v_fma_f32 v36, -v24, v27, v26
	v_fmac_f32_e32 v27, v36, v25
	v_fma_f32 v24, -v24, v27, v26
	v_div_fmas_f32 v24, v24, v25, v27
	v_div_fixup_f32 v20, v24, v20, v23
	v_lshlrev_b32_e32 v24, 16, v22
	v_and_b32_e32 v25, 0xffff0000, v22
	v_mul_f32_e32 v22, 0xbfb8aa3b, v24
	v_mul_f32_e32 v23, 0xbfb8aa3b, v25
	v_exp_f32_e32 v22, v22
	v_exp_f32_e32 v23, v23
	v_pk_mul_f32 v[20:21], v[16:17], v[20:21]
	v_pk_mul_f32 v[16:17], v[28:29], v[34:35] op_sel_hi:[1,0]
	v_pk_add_f32 v[22:23], v[22:23], 1.0 op_sel_hi:[1,0]
	s_nop 0
	v_div_scale_f32 v26, s[0:1], v23, v23, v25
	v_rcp_f32_e32 v27, v26
	s_nop 0
	v_fma_f32 v28, -v26, v27, 1.0
	v_fmac_f32_e32 v27, v28, v27
	v_div_scale_f32 v28, vcc, v25, v23, v25
	v_mul_f32_e32 v29, v28, v27
	v_fma_f32 v36, -v26, v29, v28
	v_fmac_f32_e32 v29, v36, v27
	v_fma_f32 v26, -v26, v29, v28
	v_div_fmas_f32 v26, v26, v27, v29
	v_div_fixup_f32 v23, v26, v23, v25
	v_div_scale_f32 v25, s[0:1], v22, v22, v24
	v_rcp_f32_e32 v26, v25
	s_nop 0
	v_fma_f32 v27, -v25, v26, 1.0
	v_fmac_f32_e32 v26, v27, v26
	v_div_scale_f32 v27, vcc, v24, v22, v24
	v_mul_f32_e32 v28, v27, v26
	v_fma_f32 v29, -v25, v28, v27
	v_fmac_f32_e32 v28, v29, v26
	v_fma_f32 v25, -v25, v28, v27
	v_div_fmas_f32 v25, v25, v26, v28
	v_lshlrev_b32_e32 v26, 16, v35
	v_and_b32_e32 v27, 0xffff0000, v35
	v_div_fixup_f32 v22, v25, v22, v24
	v_mul_f32_e32 v24, 0xbfb8aa3b, v26
	v_mul_f32_e32 v25, 0xbfb8aa3b, v27
	v_exp_f32_e32 v24, v24
	v_exp_f32_e32 v25, v25
	v_pk_mul_f32 v[22:23], v[16:17], v[22:23]
	v_pk_mul_f32 v[16:17], v[30:31], v[34:35] op_sel_hi:[1,0]
	v_pk_add_f32 v[24:25], v[24:25], 1.0 op_sel_hi:[1,0]
	s_nop 0
	v_div_scale_f32 v28, s[0:1], v25, v25, v27
	v_rcp_f32_e32 v29, v28
	s_nop 0
	v_fma_f32 v30, -v28, v29, 1.0
	v_fmac_f32_e32 v29, v30, v29
	v_div_scale_f32 v30, vcc, v27, v25, v27
	v_mul_f32_e32 v31, v30, v29
	v_fma_f32 v35, -v28, v31, v30
	v_fmac_f32_e32 v31, v35, v29
	v_fma_f32 v28, -v28, v31, v30
	v_div_fmas_f32 v28, v28, v29, v31
	v_div_fixup_f32 v25, v28, v25, v27
	v_div_scale_f32 v27, s[0:1], v24, v24, v26
	v_rcp_f32_e32 v28, v27
	v_pk_mul_f32 v[0:1], v[0:1], v[34:35] op_sel_hi:[1,0]
	v_pk_mul_f32 v[2:3], v[2:3], v[34:35] op_sel_hi:[1,0]
	v_pk_mul_f32 v[4:5], v[4:5], v[34:35] op_sel_hi:[1,0]
	v_fma_f32 v29, -v27, v28, 1.0
	v_fmac_f32_e32 v28, v29, v28
	v_div_scale_f32 v29, vcc, v26, v24, v26
	v_mul_f32_e32 v30, v29, v28
	v_fma_f32 v31, -v27, v30, v29
	v_fmac_f32_e32 v30, v31, v28
	v_fma_f32 v27, -v27, v30, v29
	v_div_fmas_f32 v27, v27, v28, v30
	v_div_fixup_f32 v24, v27, v24, v26
	v_pk_mul_f32 v[24:25], v[16:17], v[24:25]
	v_cvt_pk_bf16_f32 v16, v18, v19
	v_cvt_pk_bf16_f32 v17, v20, v21
	v_cvt_pk_bf16_f32 v18, v22, v23
	v_cvt_pk_bf16_f32 v19, v24, v25
	s_nop 0
	v_permlane32_swap_b32_e32 v16, v18
	v_permlane32_swap_b32_e32 v17, v19
	global_store_dwordx4 v[32:33], v[16:19], off offset:32
	v_pk_mul_f32 v[6:7], v[6:7], v[34:35] op_sel_hi:[1,0]
	s_waitcnt vmcnt(3)
	v_mov_b32_e32 v20, v70
	s_nop 1
	v_mov_b32_e32 v16, v68
	s_nop 1
	v_permlane32_swap_b32_e32 v16, v20
	v_lshlrev_b32_e32 v22, 16, v16
	v_and_b32_e32 v16, 0xffff0000, v16
	v_mov_b32_e32 v21, v71
	v_mul_f32_e32 v18, 0xbfb8aa3b, v22
	v_mul_f32_e32 v19, 0xbfb8aa3b, v16
	v_exp_f32_e32 v18, v18
	v_exp_f32_e32 v19, v19
	v_mov_b32_e32 v17, v69
	s_nop 1
	v_permlane32_swap_b32_e32 v17, v21
	v_pk_add_f32 v[18:19], v[18:19], 1.0 op_sel_hi:[1,0]
	s_nop 0
	v_div_scale_f32 v23, s[0:1], v19, v19, v16
	v_rcp_f32_e32 v24, v23
	s_nop 0
	v_fma_f32 v25, -v23, v24, 1.0
	v_fmac_f32_e32 v24, v25, v24
	v_div_scale_f32 v25, vcc, v16, v19, v16
	v_mul_f32_e32 v26, v25, v24
	v_fma_f32 v27, -v23, v26, v25
	v_fmac_f32_e32 v26, v27, v24
	v_fma_f32 v23, -v23, v26, v25
	v_div_fmas_f32 v23, v23, v24, v26
	v_div_fixup_f32 v19, v23, v19, v16
	v_div_scale_f32 v16, s[0:1], v18, v18, v22
	v_rcp_f32_e32 v23, v16
	s_nop 0
	v_fma_f32 v24, -v16, v23, 1.0
	v_fmac_f32_e32 v23, v24, v23
	v_div_scale_f32 v24, vcc, v22, v18, v22
	v_mul_f32_e32 v25, v24, v23
	v_fma_f32 v26, -v16, v25, v24
	v_fmac_f32_e32 v25, v26, v23
	v_fma_f32 v16, -v16, v25, v24
	v_div_fmas_f32 v16, v16, v23, v25
	v_div_fixup_f32 v18, v16, v18, v22
	v_pk_mul_f32 v[0:1], v[0:1], v[18:19]
	v_lshlrev_b32_e32 v18, 16, v17
	v_and_b32_e32 v19, 0xffff0000, v17
	v_mul_f32_e32 v16, 0xbfb8aa3b, v18
	v_mul_f32_e32 v17, 0xbfb8aa3b, v19
	v_exp_f32_e32 v16, v16
	v_exp_f32_e32 v17, v17
	v_cvt_pk_bf16_f32 v0, v0, v1
	v_pk_add_f32 v[16:17], v[16:17], 1.0 op_sel_hi:[1,0]
	s_nop 0
	v_div_scale_f32 v22, s[0:1], v17, v17, v19
	v_rcp_f32_e32 v23, v22
	s_nop 0
	v_fma_f32 v24, -v22, v23, 1.0
	v_fmac_f32_e32 v23, v24, v23
	v_div_scale_f32 v24, vcc, v19, v17, v19
	v_mul_f32_e32 v25, v24, v23
	v_fma_f32 v26, -v22, v25, v24
	v_fmac_f32_e32 v25, v26, v23
	v_fma_f32 v22, -v22, v25, v24
	v_div_fmas_f32 v22, v22, v23, v25
	v_div_fixup_f32 v17, v22, v17, v19
	v_div_scale_f32 v19, s[0:1], v16, v16, v18
	v_rcp_f32_e32 v22, v19
	s_nop 0
	v_fma_f32 v23, -v19, v22, 1.0
	v_fmac_f32_e32 v22, v23, v22
	v_div_scale_f32 v23, vcc, v18, v16, v18
	v_mul_f32_e32 v24, v23, v22
	v_fma_f32 v25, -v19, v24, v23
	v_fmac_f32_e32 v24, v25, v22
	v_fma_f32 v19, -v19, v24, v23
	v_div_fmas_f32 v19, v19, v22, v24
	v_div_fixup_f32 v16, v19, v16, v18
	v_lshlrev_b32_e32 v18, 16, v20
	v_and_b32_e32 v19, 0xffff0000, v20
	v_pk_mul_f32 v[2:3], v[2:3], v[16:17]
	v_mul_f32_e32 v16, 0xbfb8aa3b, v18
	v_mul_f32_e32 v17, 0xbfb8aa3b, v19
	v_exp_f32_e32 v16, v16
	v_exp_f32_e32 v17, v17
	v_cvt_pk_bf16_f32 v1, v2, v3
	v_pk_add_f32 v[16:17], v[16:17], 1.0 op_sel_hi:[1,0]
	s_nop 0
	v_div_scale_f32 v20, s[0:1], v17, v17, v19
	v_rcp_f32_e32 v22, v20
	s_nop 0
	v_fma_f32 v23, -v20, v22, 1.0
	v_fmac_f32_e32 v22, v23, v22
	v_div_scale_f32 v23, vcc, v19, v17, v19
	v_mul_f32_e32 v24, v23, v22
	v_fma_f32 v25, -v20, v24, v23
	v_fmac_f32_e32 v24, v25, v22
	v_fma_f32 v20, -v20, v24, v23
	v_div_fmas_f32 v20, v20, v22, v24
	v_div_fixup_f32 v17, v20, v17, v19
	v_div_scale_f32 v19, s[0:1], v16, v16, v18
	v_rcp_f32_e32 v20, v19
	s_nop 0
	v_fma_f32 v22, -v19, v20, 1.0
	v_fmac_f32_e32 v20, v22, v20
	v_div_scale_f32 v22, vcc, v18, v16, v18
	v_mul_f32_e32 v23, v22, v20
	v_fma_f32 v24, -v19, v23, v22
	v_fmac_f32_e32 v23, v24, v20
	v_fma_f32 v19, -v19, v23, v22
	v_div_fmas_f32 v19, v19, v20, v23
	v_div_fixup_f32 v16, v19, v16, v18
	v_lshlrev_b32_e32 v18, 16, v21
	v_and_b32_e32 v19, 0xffff0000, v21
	v_pk_mul_f32 v[4:5], v[4:5], v[16:17]
	v_mul_f32_e32 v16, 0xbfb8aa3b, v18
	v_mul_f32_e32 v17, 0xbfb8aa3b, v19
	v_exp_f32_e32 v16, v16
	v_exp_f32_e32 v17, v17
	v_cvt_pk_bf16_f32 v2, v4, v5
	s_nop 1
	v_permlane32_swap_b32_e32 v0, v2
	v_pk_add_f32 v[16:17], v[16:17], 1.0 op_sel_hi:[1,0]
	s_nop 0
	v_div_scale_f32 v20, s[0:1], v17, v17, v19
	v_rcp_f32_e32 v21, v20
	s_nop 0
	v_fma_f32 v22, -v20, v21, 1.0
	v_fmac_f32_e32 v21, v22, v21
	v_div_scale_f32 v22, vcc, v19, v17, v19
	v_mul_f32_e32 v23, v22, v21
	v_fma_f32 v24, -v20, v23, v22
	v_fmac_f32_e32 v23, v24, v21
	v_fma_f32 v20, -v20, v23, v22
	v_div_fmas_f32 v20, v20, v21, v23
	v_div_fixup_f32 v17, v20, v17, v19
	v_div_scale_f32 v19, s[0:1], v16, v16, v18
	v_rcp_f32_e32 v20, v19
	s_nop 0
	v_fma_f32 v21, -v19, v20, 1.0
	v_fmac_f32_e32 v20, v21, v20
	v_div_scale_f32 v21, vcc, v18, v16, v18
	v_mul_f32_e32 v22, v21, v20
	v_fma_f32 v23, -v19, v22, v21
	v_fmac_f32_e32 v22, v23, v20
	v_fma_f32 v19, -v19, v22, v21
	v_div_fmas_f32 v19, v19, v20, v22
	v_div_fixup_f32 v16, v19, v16, v18
	v_pk_mul_f32 v[6:7], v[6:7], v[16:17]
	s_nop 0
	v_cvt_pk_bf16_f32 v3, v6, v7
	s_nop 1
	v_permlane32_swap_b32_e32 v1, v3
	global_store_dwordx4 v[32:33], v[0:3], off offset:64
	s_waitcnt vmcnt(3)
	v_mov_b32_e32 v6, v74
	s_nop 1
	v_mov_b32_e32 v0, v72
	s_nop 1
	v_permlane32_swap_b32_e32 v0, v6
	v_lshlrev_b32_e32 v7, 16, v0
	v_and_b32_e32 v0, 0xffff0000, v0
	v_mul_f32_e32 v4, 0xbfb8aa3b, v7
	v_mul_f32_e32 v5, 0xbfb8aa3b, v0
	v_exp_f32_e32 v4, v4
	v_exp_f32_e32 v5, v5
	v_mov_b32_e32 v16, v75
	v_pk_mul_f32 v[2:3], v[8:9], v[34:35] op_sel_hi:[1,0]
	s_nop 0
	v_mov_b32_e32 v1, v73
	s_nop 1
	v_permlane32_swap_b32_e32 v1, v16
	v_pk_add_f32 v[4:5], v[4:5], 1.0 op_sel_hi:[1,0]
	s_nop 0
	v_div_scale_f32 v8, s[0:1], v5, v5, v0
	v_rcp_f32_e32 v9, v8
	s_nop 0
	v_fma_f32 v17, -v8, v9, 1.0
	v_fmac_f32_e32 v9, v17, v9
	v_div_scale_f32 v17, vcc, v0, v5, v0
	v_mul_f32_e32 v18, v17, v9
	v_fma_f32 v19, -v8, v18, v17
	v_fmac_f32_e32 v18, v19, v9
	v_fma_f32 v8, -v8, v18, v17
	v_div_fmas_f32 v8, v8, v9, v18
	v_div_fixup_f32 v5, v8, v5, v0
	v_div_scale_f32 v0, s[0:1], v4, v4, v7
	v_rcp_f32_e32 v8, v0
	s_nop 0
	v_fma_f32 v9, -v0, v8, 1.0
	v_fmac_f32_e32 v8, v9, v8
	v_div_scale_f32 v9, vcc, v7, v4, v7
	v_mul_f32_e32 v17, v9, v8
	v_fma_f32 v18, -v0, v17, v9
	v_fmac_f32_e32 v17, v18, v8
	v_fma_f32 v0, -v0, v17, v9
	v_div_fmas_f32 v0, v0, v8, v17
	v_div_fixup_f32 v4, v0, v4, v7
	v_lshlrev_b32_e32 v7, 16, v1
	v_and_b32_e32 v8, 0xffff0000, v1
	v_pk_mul_f32 v[2:3], v[2:3], v[4:5]
	v_mul_f32_e32 v4, 0xbfb8aa3b, v7
	v_mul_f32_e32 v5, 0xbfb8aa3b, v8
	v_exp_f32_e32 v4, v4
	v_exp_f32_e32 v5, v5
	v_pk_mul_f32 v[0:1], v[10:11], v[34:35] op_sel_hi:[1,0]
	v_pk_add_f32 v[4:5], v[4:5], 1.0 op_sel_hi:[1,0]
	s_nop 0
	v_div_scale_f32 v9, s[0:1], v5, v5, v8
	v_rcp_f32_e32 v10, v9
	s_nop 0
	v_fma_f32 v11, -v9, v10, 1.0
	v_fmac_f32_e32 v10, v11, v10
	v_div_scale_f32 v11, vcc, v8, v5, v8
	v_mul_f32_e32 v17, v11, v10
	v_fma_f32 v18, -v9, v17, v11
	v_fmac_f32_e32 v17, v18, v10
	v_fma_f32 v9, -v9, v17, v11
	v_div_fmas_f32 v9, v9, v10, v17
	v_div_fixup_f32 v5, v9, v5, v8
	v_div_scale_f32 v8, s[0:1], v4, v4, v7
	v_rcp_f32_e32 v9, v8
	s_nop 0
	v_fma_f32 v10, -v8, v9, 1.0
	v_fmac_f32_e32 v9, v10, v9
	v_div_scale_f32 v10, vcc, v7, v4, v7
	v_mul_f32_e32 v11, v10, v9
	v_fma_f32 v17, -v8, v11, v10
	v_fmac_f32_e32 v11, v17, v9
	v_fma_f32 v8, -v8, v11, v10
	v_div_fmas_f32 v8, v8, v9, v11
	v_div_fixup_f32 v4, v8, v4, v7
	v_lshlrev_b32_e32 v8, 16, v6
	v_and_b32_e32 v9, 0xffff0000, v6
	v_mul_f32_e32 v6, 0xbfb8aa3b, v8
	v_mul_f32_e32 v7, 0xbfb8aa3b, v9
	v_exp_f32_e32 v6, v6
	v_exp_f32_e32 v7, v7
	v_pk_mul_f32 v[4:5], v[0:1], v[4:5]
	v_pk_mul_f32 v[0:1], v[12:13], v[34:35] op_sel_hi:[1,0]
	v_pk_add_f32 v[6:7], v[6:7], 1.0 op_sel_hi:[1,0]
	s_nop 0
	v_div_scale_f32 v10, s[0:1], v7, v7, v9
	v_rcp_f32_e32 v11, v10
	s_nop 0
	v_fma_f32 v12, -v10, v11, 1.0
	v_fmac_f32_e32 v11, v12, v11
	v_div_scale_f32 v12, vcc, v9, v7, v9
	v_mul_f32_e32 v13, v12, v11
	v_fma_f32 v17, -v10, v13, v12
	v_fmac_f32_e32 v13, v17, v11
	v_fma_f32 v10, -v10, v13, v12
	v_div_fmas_f32 v10, v10, v11, v13
	v_div_fixup_f32 v7, v10, v7, v9
	v_div_scale_f32 v9, s[0:1], v6, v6, v8
	v_rcp_f32_e32 v10, v9
	s_nop 0
	v_fma_f32 v11, -v9, v10, 1.0
	v_fmac_f32_e32 v10, v11, v10
	v_div_scale_f32 v11, vcc, v8, v6, v8
	v_mul_f32_e32 v12, v11, v10
	v_fma_f32 v13, -v9, v12, v11
	v_fmac_f32_e32 v12, v13, v10
	v_fma_f32 v9, -v9, v12, v11
	v_div_fmas_f32 v9, v9, v10, v12
	v_lshlrev_b32_e32 v10, 16, v16
	v_and_b32_e32 v11, 0xffff0000, v16
	v_div_fixup_f32 v6, v9, v6, v8
	v_mul_f32_e32 v8, 0xbfb8aa3b, v10
	v_mul_f32_e32 v9, 0xbfb8aa3b, v11
	v_exp_f32_e32 v8, v8
	v_exp_f32_e32 v9, v9
	v_pk_mul_f32 v[6:7], v[0:1], v[6:7]
	v_pk_mul_f32 v[0:1], v[14:15], v[34:35] op_sel_hi:[1,0]
	v_pk_add_f32 v[8:9], v[8:9], 1.0 op_sel_hi:[1,0]
	s_nop 0
	v_div_scale_f32 v12, s[0:1], v9, v9, v11
	v_rcp_f32_e32 v13, v12
	s_nop 0
	v_fma_f32 v14, -v12, v13, 1.0
	v_fmac_f32_e32 v13, v14, v13
	v_div_scale_f32 v14, vcc, v11, v9, v11
	v_mul_f32_e32 v15, v14, v13
	v_fma_f32 v16, -v12, v15, v14
	v_fmac_f32_e32 v15, v16, v13
	v_fma_f32 v12, -v12, v15, v14
	v_div_fmas_f32 v12, v12, v13, v15
	v_div_fixup_f32 v9, v12, v9, v11
	v_div_scale_f32 v11, s[0:1], v8, v8, v10
	v_rcp_f32_e32 v12, v11
	s_nop 0
	v_fma_f32 v13, -v11, v12, 1.0
	v_fmac_f32_e32 v12, v13, v12
	v_div_scale_f32 v13, vcc, v10, v8, v10
	v_mul_f32_e32 v14, v13, v12
	v_fma_f32 v15, -v11, v14, v13
	v_fmac_f32_e32 v14, v15, v12
	v_fma_f32 v11, -v11, v14, v13
	v_div_fmas_f32 v11, v11, v12, v14
	v_div_fixup_f32 v8, v11, v8, v10
	v_pk_mul_f32 v[8:9], v[0:1], v[8:9]
	v_cvt_pk_bf16_f32 v0, v2, v3
	v_cvt_pk_bf16_f32 v1, v4, v5
	v_cvt_pk_bf16_f32 v2, v6, v7
	v_cvt_pk_bf16_f32 v3, v8, v9
	s_nop 0
	v_permlane32_swap_b32_e32 v0, v2
	v_permlane32_swap_b32_e32 v1, v3
	global_store_dwordx4 v[32:33], v[0:3], off offset:96
